# s2 + tail0: w_br transposes spread over all 256 workgroups + tail0 block loads as global with counted vmcnt waits
# baseline (speedup 1.0000x reference)
; #define LAS __attribute__((address_space(3)))
; __device__ __forceinline__ void phase_tail_transposes(LAS unsigned char* lds, int part, int wv) {
;     const Ctx c = fresh_ctx(wv);
;     constexpr int NB1 = NI8 / 32, NBO = DM / 32, NT0 = 128;
;     if (part == 0) {
;         if (c.G != 256) { bf16_tiles(c, 0, 7168, 11264, c.gw, c.NGW); for (int cb = c.vcu; cb < NT0; cb += c.G) direct_win_block(c, lds, 1, cb); return; }
;         if (c.vcu < 192) return;
;         bf16_tiles(c, 0, 7168, 11264, (c.vcu - 192) * NWAVES + c.wave, 64 * NWAVES);
;         for (int cb = c.vcu - 192; cb < NT0; cb += 64) direct_win_block(c, lds, 1, cb);
;         return; }
.LBB0_433:
	s_and_b64 vcc, exec, s[4:5]
	s_cbranch_vccz .LBB0_457
	s_mov_b32 s1, s2
	v_lshlrev_b32_e32 v0, 2, v168
	s_cmpk_gt_i32 s1, 0xfff
	v_and_b32_e32 v32, 56, v169
	v_and_b32_e32 v33, 28, v0
	s_cbranch_scc1 .LBB0_450
	s_addk_i32 s1, 0x1c00
	s_waitcnt lgkmcnt(0)
	s_add_u32 s4, s10, 0x1a001800
	s_addc_u32 s5, s11, 0
	s_add_u32 s6, s10, 0x1a001000
	s_addc_u32 s7, s11, 0
	s_add_u32 s8, s10, 0x1a000000
	s_addc_u32 s9, s11, 0
	s_add_u32 s12, s10, 0x2000000
	v_or_b32_e32 v38, 0xffffd800, v32
	s_addc_u32 s13, s11, 0
	s_lshl_b32 s2, s1, 6
	s_branch .LBB0_438
.LBB0_437:
	s_add_i32 s3, s1, 0x800
	s_add_i32 s2, s2, 0x20000
	s_cmpk_lt_i32 s1, 0x2400
	s_mov_b32 s1, s3
	s_cbranch_scc0 .LBB0_450

; #define LAS __attribute__((address_space(3)))
; __device__ __forceinline__ float bflo(unsigned w) { return __uint_as_float(w << 16); }
; __device__ __forceinline__ float bfhi(unsigned w) { return __uint_as_float(w & 0xffff0000u); }
; __device__ __forceinline__ void direct_w8_block(const Ctx& c, LAS unsigned char* lds, const float* Wsrc, const int INC_, int srccol, unsigned char* dstrow, float* swdst) {
;     ...
;     f32x4 sc, inv;
; #pragma unroll
;     for (int j = 0; j < 4; ++j) { sc[j] = cm[j] > 0.f ? cm[j] * (1.0f / 127.0f) : 1.0f; inv[j] = 1.0f / sc[j]; }
;     if (wave == 0 && kr == 0) *(f32x4*)(swdst + 4 * nc) = sc;
;     unsigned char* dst = dstrow + (size_t)(4 * nc) * DM + 512 * wave + 8 * kr;
; #pragma unroll
;     for (int t = 0; t < 8; ++t) { unsigned char* dt = dst + t * 64; asm volatile("" : "+v"(dt));
; #pragma unroll
;         for (int j = 0; j < 4; ++j) { v4u pk;
;             if (t < 4) { pk.x = held[t & 3][j][0]; pk.y = held[t & 3][j][1]; pk.z = held[t & 3][j][2]; pk.w = held[t & 3][j][3]; }
;             else pk = *(const LAS v4u*)(hl + ((t - 4) * 4 + j) * 1024);
;             int qi[8];
; #pragma unroll
;             for (int pr = 0; pr < 4; ++pr) { qi[2 * pr] = __float2int_rn(bflo(pk[pr]) * inv[j]); qi[2 * pr + 1] = __float2int_rn(bfhi(pk[pr]) * inv[j]); }
;             v2u w; w.x = (unsigned)(qi[0] & 255) | ((unsigned)(qi[1] & 255) << 8) | ((unsigned)(qi[2] & 255) << 16) | ((unsigned)(qi[3] & 255) << 24);
;             w.y = (unsigned)(qi[4] & 255) | ((unsigned)(qi[5] & 255) << 8) | ((unsigned)(qi[6] & 255) << 16) | ((unsigned)(qi[7] & 255) << 24);
;             *(v2u*)(dt + (size_t)j * DM) = w; } }
; __device__ __forceinline__ void phase_tail_transposes(LAS unsigned char* lds, int part, int wv) {
;     ...
;         if (c.G != 256) { bf16_tiles(c, 0, 7168, 11264, c.gw, c.NGW); for (int cb = c.vcu; cb < NT0; cb += c.G) direct_win_block(c, lds, 1, cb); return; }
;         if (c.vcu < 192) return;
;         bf16_tiles(c, 0, 7168, 11264, (c.vcu - 192) * NWAVES + c.wave, 64 * NWAVES);
;         for (int cb = c.vcu - 192; cb < NT0; cb += 64) direct_win_block(c, lds, 1, cb);
.LBB0_450:
	s_cmpk_lt_i32 s0, 0xc0
	s_cbranch_scc1 .LBB0_457
	s_cmpk_gt_i32 s0, 0x13f
	s_cbranch_scc1 .LBB0_457
	s_load_dwordx2 s[2:3], s[14:15], 0x30
	v_readlane_b32 s8, v254, 13
	v_lshlrev_b32_e32 v96, 2, v33
	v_readlane_b32 s1, v254, 12
	v_or_b32_e32 v2, s8, v32
	s_waitcnt lgkmcnt(0)
	v_mov_b64_e32 v[0:1], s[2:3]
	v_mad_u64_u32 v[0:1], s[2:3], v2, s61, v[0:1]
	v_lshl_add_u64 v[0:1], v[0:1], 0, v[96:97]
	s_mov_b64 s[2:3], 0x18000000
	v_lshl_add_u64 v[162:163], v[0:1], 0, s[2:3]
	v_readlane_b32 s2, v254, 4
	v_lshlrev_b32_e32 v3, 4, v168
	v_cmp_gt_u32_e64 s[6:7], 8, v168
	v_add_u32_e32 v168, s1, v96
	s_add_i32 s1, 0, 0x20800
	v_readlane_b32 s3, v254, 5
	v_add_u32_e32 v169, s1, v96
	s_and_b64 s[4:5], s[2:3], s[6:7]
	v_lshl_add_u64 v[0:1], s[10:11], 0, v[96:97]
	s_mov_b64 s[2:3], 0x6ff11000
	v_lshlrev_b32_e32 v96, 12, v33
	v_readlane_b32 s9, v254, 14
	v_lshl_add_u64 v[164:165], v[0:1], 0, s[2:3]
	v_lshl_add_u64 v[0:1], s[10:11], 0, v[96:97]
	v_lshl_add_u64 v[0:1], v[0:1], 0, s[8:9]
	v_mov_b32_e32 v33, v97
	v_lshl_add_u64 v[0:1], v[0:1], 0, v[32:33]
	s_mov_b64 s[2:3], 0x6b800000
	s_add_i32 s1, s0, 0xffffff00
	s_lshl_b32 s0, s0, 5
	v_lshl_add_u64 v[166:167], v[0:1], 0, s[2:3]
	s_add_i32 s10, s0, 0xffffe800
	v_add_u32_e32 v96, s52, v3
	s_mov_b32 s0, 0x48000
	s_branch .LBB0_453
.LBB0_452:
	s_or_b64 exec, exec, s[8:9]
	v_div_scale_f32 v134, s[2:3], v130, v130, 1.0
	v_rcp_f32_e32 v135, v134
	v_cvt_pk_bf16_f32 v4, v0, v4
	v_cvt_pk_bf16_f32 v8, v8, v12
	v_lshlrev_b32_e32 v12, 16, v4
	v_fma_f32 v136, -v134, v135, 1.0
	v_fmac_f32_e32 v135, v136, v135
	v_div_scale_f32 v136, vcc, 1.0, v130, 1.0
	v_mul_f32_e32 v137, v136, v135
	v_fma_f32 v138, -v134, v137, v136
	v_fmac_f32_e32 v137, v138, v135
	v_fma_f32 v134, -v134, v137, v136
	v_div_fmas_f32 v134, v134, v135, v137
	v_div_fixup_f32 v135, v134, v130, 1.0
	v_div_scale_f32 v130, s[2:3], v131, v131, 1.0
	v_rcp_f32_e32 v134, v130
	v_and_b32_e32 v4, 0xffff0000, v4
	v_cvt_pk_bf16_f32 v11, v11, v15
	v_cvt_pk_bf16_f32 v15, v3, v7
	v_fma_f32 v136, -v130, v134, 1.0
	v_fmac_f32_e32 v134, v136, v134
	v_div_scale_f32 v136, vcc, 1.0, v131, 1.0
	v_mul_f32_e32 v137, v136, v134
	v_fma_f32 v138, -v130, v137, v136
	v_fmac_f32_e32 v137, v138, v134
	v_fma_f32 v130, -v130, v137, v136
	v_div_fmas_f32 v130, v130, v134, v137
	v_div_fixup_f32 v134, v130, v131, 1.0
	v_div_scale_f32 v130, s[2:3], v132, v132, 1.0
	v_rcp_f32_e32 v131, v130
	v_cvt_pk_bf16_f32 v7, v17, v21
	v_cvt_pk_bf16_f32 v16, v16, v20
	v_mul_f32_e32 v4, v135, v4
	v_fma_f32 v136, -v130, v131, 1.0
	v_lshlrev_b32_e32 v17, 16, v8
	v_and_b32_e32 v8, 0xffff0000, v8
	v_fmac_f32_e32 v131, v136, v131
	v_div_scale_f32 v136, vcc, 1.0, v132, 1.0
	v_cvt_pk_bf16_f32 v9, v9, v13
	v_cvt_pk_bf16_f32 v13, v1, v5
	v_cvt_pk_bf16_f32 v5, v24, v28
	v_mul_f32_e32 v12, v135, v12
	v_rndne_f32_e32 v4, v4
	v_mul_f32_e32 v17, v135, v17
	v_mul_f32_e32 v8, v135, v8
	v_lshlrev_b32_e32 v20, 16, v16
	v_and_b32_e32 v16, 0xffff0000, v16
	v_mul_f32_e32 v137, v136, v131
	v_rndne_f32_e32 v12, v12
	v_cvt_i32_f32_e32 v4, v4
	v_rndne_f32_e32 v17, v17
	v_rndne_f32_e32 v8, v8
	v_mul_f32_e32 v16, v135, v16
	v_lshlrev_b32_e32 v21, 16, v5
	v_and_b32_e32 v5, 0xffff0000, v5
	v_fma_f32 v138, -v130, v137, v136
	v_cvt_i32_f32_e32 v12, v12
	v_cvt_i32_f32_sdwa v17, v17 dst_sel:WORD_1 dst_unused:UNUSED_PAD src0_sel:DWORD
	v_cvt_i32_f32_e32 v8, v8
	v_mul_f32_e32 v20, v135, v20
	v_rndne_f32_e32 v16, v16
	v_mul_f32_e32 v21, v135, v21
	v_mul_f32_e32 v5, v135, v5
	v_fmac_f32_e32 v137, v138, v131
	v_rndne_f32_e32 v20, v20
	v_cvt_i32_f32_e32 v16, v16
	v_rndne_f32_e32 v21, v21
	v_rndne_f32_e32 v5, v5
	v_fma_f32 v130, -v130, v137, v136
	v_cvt_i32_f32_e32 v20, v20
	v_cvt_i32_f32_sdwa v21, v21 dst_sel:WORD_1 dst_unused:UNUSED_PAD src0_sel:DWORD
	v_cvt_i32_f32_e32 v5, v5
	v_div_fmas_f32 v130, v130, v131, v137
	v_lshlrev_b32_e32 v4, 8, v4
	v_div_fixup_f32 v131, v130, v132, 1.0
	v_div_scale_f32 v130, s[2:3], v133, v133, 1.0
	v_and_b32_e32 v4, 0xff00, v4
	v_and_b32_e32 v17, 0xff0000, v17
	v_perm_b32 v8, v8, v12, s81
	s_lshl_b64 s[2:3], s[10:11], 12
	v_or3_b32 v4, v8, v4, v17
	v_lshlrev_b32_e32 v8, 8, v16
	v_lshl_add_u64 v[0:1], v[166:167], 0, s[2:3]
	v_and_b32_e32 v8, 0xff00, v8
	v_and_b32_e32 v12, 0xff0000, v21
	v_perm_b32 v5, v5, v20, s81
	v_cvt_pk_bf16_f32 v10, v10, v14
	v_cvt_pk_bf16_f32 v14, v2, v6
	v_mov_b64_e32 v[2:3], v[0:1]
	v_or3_b32 v5, v5, v8, v12
	global_store_dwordx2 v[2:3], v[4:5], off
	v_and_b32_e32 v5, 0xffff0000, v13
	v_rcp_f32_e32 v132, v130
	v_lshlrev_b32_e32 v4, 16, v13
	v_mul_f32_e32 v5, v134, v5
	v_lshlrev_b32_e32 v8, 16, v9
	v_and_b32_e32 v9, 0xffff0000, v9
	v_cvt_pk_bf16_f32 v6, v25, v29
	v_mul_f32_e32 v4, v134, v4
	v_rndne_f32_e32 v5, v5
	v_mul_f32_e32 v8, v134, v8
	v_mul_f32_e32 v9, v134, v9
	v_lshlrev_b32_e32 v12, 16, v7
	v_and_b32_e32 v7, 0xffff0000, v7
	v_rndne_f32_e32 v4, v4
	v_cvt_i32_f32_e32 v5, v5
	v_rndne_f32_e32 v8, v8
	v_rndne_f32_e32 v9, v9
	v_mul_f32_e32 v7, v134, v7
	v_lshlrev_b32_e32 v13, 16, v6
	v_and_b32_e32 v6, 0xffff0000, v6
	v_cvt_i32_f32_e32 v4, v4
	v_cvt_i32_f32_sdwa v8, v8 dst_sel:WORD_1 dst_unused:UNUSED_PAD src0_sel:DWORD
	v_cvt_i32_f32_e32 v9, v9
	v_mul_f32_e32 v12, v134, v12
	v_rndne_f32_e32 v7, v7
	v_mul_f32_e32 v13, v134, v13
	v_mul_f32_e32 v6, v134, v6
	v_fma_f32 v136, -v130, v132, 1.0
	v_rndne_f32_e32 v12, v12
	v_cvt_i32_f32_e32 v7, v7
	v_rndne_f32_e32 v13, v13
	v_rndne_f32_e32 v6, v6
	v_fmac_f32_e32 v132, v136, v132
	v_div_scale_f32 v136, vcc, 1.0, v133, 1.0
	v_cvt_i32_f32_e32 v12, v12
	v_cvt_i32_f32_sdwa v13, v13 dst_sel:WORD_1 dst_unused:UNUSED_PAD src0_sel:DWORD
	v_cvt_i32_f32_e32 v6, v6
	v_mul_f32_e32 v137, v136, v132
	v_lshlrev_b32_e32 v5, 8, v5
	v_fma_f32 v138, -v130, v137, v136
; #define LAS __attribute__((address_space(3)))
; __device__ __forceinline__ float bflo(unsigned w) { return __uint_as_float(w << 16); }
; __device__ __forceinline__ float bfhi(unsigned w) { return __uint_as_float(w & 0xffff0000u); }
; __device__ __forceinline__ void direct_w8_block(const Ctx& c, LAS unsigned char* lds, const float* Wsrc, const int INC_, int srccol, unsigned char* dstrow, float* swdst) {
;     ...
;         for (int j = 0; j < 4; ++j) { v4u pk;
;             if (t < 4) { pk.x = held[t & 3][j][0]; pk.y = held[t & 3][j][1]; pk.z = held[t & 3][j][2]; pk.w = held[t & 3][j][3]; }
;             else pk = *(const LAS v4u*)(hl + ((t - 4) * 4 + j) * 1024);
;             int qi[8];
; #pragma unroll
;             for (int pr = 0; pr < 4; ++pr) { qi[2 * pr] = __float2int_rn(bflo(pk[pr]) * inv[j]); qi[2 * pr + 1] = __float2int_rn(bfhi(pk[pr]) * inv[j]); }
;             v2u w; w.x = (unsigned)(qi[0] & 255) | ((unsigned)(qi[1] & 255) << 8) | ((unsigned)(qi[2] & 255) << 16) | ((unsigned)(qi[3] & 255) << 24);
;             w.y = (unsigned)(qi[4] & 255) | ((unsigned)(qi[5] & 255) << 8) | ((unsigned)(qi[6] & 255) << 16) | ((unsigned)(qi[7] & 255) << 24);
;             *(v2u*)(dt + (size_t)j * DM) = w; } }
	v_and_b32_e32 v5, 0xff00, v5
	v_and_b32_e32 v8, 0xff0000, v8
	v_perm_b32 v4, v9, v4, s81
	v_fmac_f32_e32 v137, v138, v132
	v_or3_b32 v4, v4, v5, v8
	v_lshlrev_b32_e32 v5, 8, v7
	v_fma_f32 v130, -v130, v137, v136
	v_and_b32_e32 v5, 0xff00, v5
	v_and_b32_e32 v7, 0xff0000, v13
	v_perm_b32 v6, v6, v12, s81
	v_div_fmas_f32 v130, v130, v132, v137
	v_or3_b32 v5, v6, v5, v7
	v_add_co_u32_e32 v6, vcc, s67, v2
	v_cvt_pk_bf16_f32 v18, v18, v22
	s_nop 0
	v_addc_co_u32_e32 v7, vcc, 0, v3, vcc
	global_store_dwordx2 v[6:7], v[4:5], off
	v_and_b32_e32 v5, 0xffff0000, v14
	v_lshlrev_b32_e32 v4, 16, v14
	v_mul_f32_e32 v5, v131, v5
	v_lshlrev_b32_e32 v6, 16, v10
	v_and_b32_e32 v7, 0xffff0000, v10
	v_cvt_pk_bf16_f32 v19, v19, v23
	v_cvt_pk_bf16_f32 v23, v26, v30
	v_mul_f32_e32 v4, v131, v4
	v_rndne_f32_e32 v5, v5
	v_mul_f32_e32 v6, v131, v6
	v_mul_f32_e32 v7, v131, v7
	v_and_b32_e32 v9, 0xffff0000, v18
	v_rndne_f32_e32 v4, v4
	v_cvt_i32_f32_e32 v5, v5
	v_rndne_f32_e32 v6, v6
	v_rndne_f32_e32 v7, v7
	v_lshlrev_b32_e32 v8, 16, v18
	v_mul_f32_e32 v9, v131, v9
	v_lshlrev_b32_e32 v10, 16, v23
	v_and_b32_e32 v12, 0xffff0000, v23
	v_cvt_i32_f32_e32 v4, v4
	v_cvt_i32_f32_sdwa v6, v6 dst_sel:WORD_1 dst_unused:UNUSED_PAD src0_sel:DWORD
	v_cvt_i32_f32_e32 v7, v7
	v_mul_f32_e32 v8, v131, v8
	v_rndne_f32_e32 v9, v9
	v_mul_f32_e32 v10, v131, v10
	v_mul_f32_e32 v12, v131, v12
	v_rndne_f32_e32 v8, v8
	v_cvt_i32_f32_e32 v9, v9
	v_rndne_f32_e32 v10, v10
	v_rndne_f32_e32 v12, v12
	v_cvt_i32_f32_e32 v8, v8
	v_cvt_i32_f32_sdwa v10, v10 dst_sel:WORD_1 dst_unused:UNUSED_PAD src0_sel:DWORD
	v_cvt_i32_f32_e32 v12, v12
	v_lshlrev_b32_e32 v5, 8, v5
	v_and_b32_e32 v5, 0xff00, v5
	v_and_b32_e32 v6, 0xff0000, v6
	v_perm_b32 v4, v7, v4, s81
	v_or3_b32 v4, v4, v5, v6
	v_lshlrev_b32_e32 v5, 8, v9
	v_and_b32_e32 v5, 0xff00, v5
	v_and_b32_e32 v6, 0xff0000, v10
	v_perm_b32 v7, v12, v8, s81
	v_or3_b32 v5, v7, v5, v6
	v_add_co_u32_e32 v6, vcc, s33, v2
	v_div_fixup_f32 v130, v130, v133, 1.0
	s_nop 0
	v_addc_co_u32_e32 v7, vcc, 0, v3, vcc
	global_store_dwordx2 v[6:7], v[4:5], off
	v_and_b32_e32 v5, 0xffff0000, v15
	v_lshlrev_b32_e32 v4, 16, v15
	v_mul_f32_e32 v5, v130, v5
	v_lshlrev_b32_e32 v6, 16, v11
	v_and_b32_e32 v7, 0xffff0000, v11
	v_cvt_pk_bf16_f32 v27, v27, v31
	v_mul_f32_e32 v4, v130, v4
	v_rndne_f32_e32 v5, v5
	v_mul_f32_e32 v6, v130, v6
	v_mul_f32_e32 v7, v130, v7
	v_and_b32_e32 v9, 0xffff0000, v19
	v_rndne_f32_e32 v4, v4
	v_cvt_i32_f32_e32 v5, v5
	v_rndne_f32_e32 v6, v6
	v_rndne_f32_e32 v7, v7
	v_lshlrev_b32_e32 v8, 16, v19
	v_mul_f32_e32 v9, v130, v9
	v_lshlrev_b32_e32 v10, 16, v27
	v_and_b32_e32 v11, 0xffff0000, v27
	v_cvt_i32_f32_e32 v4, v4
	v_cvt_i32_f32_sdwa v6, v6 dst_sel:WORD_1 dst_unused:UNUSED_PAD src0_sel:DWORD
	v_cvt_i32_f32_e32 v7, v7
	v_mul_f32_e32 v8, v130, v8
	v_rndne_f32_e32 v9, v9
	v_mul_f32_e32 v10, v130, v10
	v_mul_f32_e32 v11, v130, v11
	v_rndne_f32_e32 v8, v8
	v_cvt_i32_f32_e32 v9, v9
	v_rndne_f32_e32 v10, v10
	v_rndne_f32_e32 v11, v11
	v_cvt_i32_f32_e32 v8, v8
	v_cvt_i32_f32_sdwa v10, v10 dst_sel:WORD_1 dst_unused:UNUSED_PAD src0_sel:DWORD
	v_cvt_i32_f32_e32 v11, v11
	v_lshlrev_b32_e32 v5, 8, v5
	v_and_b32_e32 v5, 0xff00, v5
	v_and_b32_e32 v6, 0xff0000, v6
	v_perm_b32 v4, v7, v4, s81
	v_or3_b32 v4, v4, v5, v6
	v_lshlrev_b32_e32 v5, 8, v9
	v_and_b32_e32 v5, 0xff00, v5
	v_and_b32_e32 v6, 0xff0000, v10
	v_perm_b32 v7, v11, v8, s81
	v_add_co_u32_e32 v2, vcc, s44, v2
	v_cvt_pk_bf16_f32 v32, v32, v36
	v_or3_b32 v5, v7, v5, v6
	v_addc_co_u32_e32 v3, vcc, 0, v3, vcc
	v_cvt_pk_bf16_f32 v40, v40, v44
	global_store_dwordx2 v[2:3], v[4:5], off
	v_and_b32_e32 v5, 0xffff0000, v32
	v_cvt_pk_bf16_f32 v41, v41, v45
	v_cvt_pk_bf16_f32 v45, v48, v52
	v_lshlrev_b32_e32 v4, 16, v32
	v_mul_f32_e32 v5, v135, v5
	v_lshlrev_b32_e32 v6, 16, v40
	v_and_b32_e32 v7, 0xffff0000, v40
	v_cvt_pk_bf16_f32 v33, v33, v37
	v_cvt_pk_bf16_f32 v37, v56, v60
	v_mul_f32_e32 v4, v135, v4
	v_rndne_f32_e32 v5, v5
	v_mul_f32_e32 v6, v135, v6
	v_mul_f32_e32 v7, v135, v7
	v_and_b32_e32 v9, 0xffff0000, v45
	v_rndne_f32_e32 v4, v4
	v_cvt_i32_f32_e32 v5, v5
	v_rndne_f32_e32 v6, v6
	v_rndne_f32_e32 v7, v7
	v_lshlrev_b32_e32 v8, 16, v45
	v_mul_f32_e32 v9, v135, v9
	v_lshlrev_b32_e32 v10, 16, v37
	v_and_b32_e32 v11, 0xffff0000, v37
	v_cvt_i32_f32_e32 v4, v4
	v_cvt_i32_f32_sdwa v6, v6 dst_sel:WORD_1 dst_unused:UNUSED_PAD src0_sel:DWORD
	v_cvt_i32_f32_e32 v7, v7
	v_mul_f32_e32 v8, v135, v8
	v_rndne_f32_e32 v9, v9
	v_mul_f32_e32 v10, v135, v10
	v_mul_f32_e32 v11, v135, v11
	v_rndne_f32_e32 v8, v8
	v_cvt_i32_f32_e32 v9, v9
	v_rndne_f32_e32 v10, v10
	v_rndne_f32_e32 v11, v11
	v_cvt_i32_f32_e32 v8, v8
	v_cvt_i32_f32_sdwa v10, v10 dst_sel:WORD_1 dst_unused:UNUSED_PAD src0_sel:DWORD
	v_cvt_i32_f32_e32 v11, v11
	v_lshlrev_b32_e32 v5, 8, v5
	v_and_b32_e32 v5, 0xff00, v5
	v_and_b32_e32 v6, 0xff0000, v6
	v_perm_b32 v4, v7, v4, s81
	v_or3_b32 v4, v4, v5, v6
	v_lshlrev_b32_e32 v5, 8, v9
	v_and_b32_e32 v5, 0xff00, v5
	v_and_b32_e32 v6, 0xff0000, v10
	v_perm_b32 v7, v11, v8, s81
	v_lshl_add_u64 v[2:3], v[0:1], 0, 64
	v_or3_b32 v5, v7, v5, v6
	global_store_dwordx2 v[2:3], v[4:5], off
	v_and_b32_e32 v5, 0xffff0000, v33
	v_cvt_pk_bf16_f32 v42, v42, v46
	v_cvt_pk_bf16_f32 v46, v49, v53
	v_lshlrev_b32_e32 v4, 16, v33
	v_mul_f32_e32 v5, v134, v5
	v_lshlrev_b32_e32 v6, 16, v41
	v_and_b32_e32 v7, 0xffff0000, v41
	v_cvt_pk_bf16_f32 v34, v34, v38
	v_cvt_pk_bf16_f32 v38, v57, v61
	v_mul_f32_e32 v4, v134, v4
	v_rndne_f32_e32 v5, v5
	v_mul_f32_e32 v6, v134, v6
	v_mul_f32_e32 v7, v134, v7
	v_and_b32_e32 v9, 0xffff0000, v46
	v_rndne_f32_e32 v4, v4
	v_cvt_i32_f32_e32 v5, v5
	v_rndne_f32_e32 v6, v6
	v_rndne_f32_e32 v7, v7
	v_lshlrev_b32_e32 v8, 16, v46
; #define LAS __attribute__((address_space(3)))
; __device__ __forceinline__ float bflo(unsigned w) { return __uint_as_float(w << 16); }
; __device__ __forceinline__ float bfhi(unsigned w) { return __uint_as_float(w & 0xffff0000u); }
; __device__ __forceinline__ void direct_w8_block(const Ctx& c, LAS unsigned char* lds, const float* Wsrc, const int INC_, int srccol, unsigned char* dstrow, float* swdst) {
;     ...
;         for (int j = 0; j < 4; ++j) { v4u pk;
;             if (t < 4) { pk.x = held[t & 3][j][0]; pk.y = held[t & 3][j][1]; pk.z = held[t & 3][j][2]; pk.w = held[t & 3][j][3]; }
;             else pk = *(const LAS v4u*)(hl + ((t - 4) * 4 + j) * 1024);
;             int qi[8];
; #pragma unroll
;             for (int pr = 0; pr < 4; ++pr) { qi[2 * pr] = __float2int_rn(bflo(pk[pr]) * inv[j]); qi[2 * pr + 1] = __float2int_rn(bfhi(pk[pr]) * inv[j]); }
;             v2u w; w.x = (unsigned)(qi[0] & 255) | ((unsigned)(qi[1] & 255) << 8) | ((unsigned)(qi[2] & 255) << 16) | ((unsigned)(qi[3] & 255) << 24);
;             w.y = (unsigned)(qi[4] & 255) | ((unsigned)(qi[5] & 255) << 8) | ((unsigned)(qi[6] & 255) << 16) | ((unsigned)(qi[7] & 255) << 24);
;             *(v2u*)(dt + (size_t)j * DM) = w; } }
	v_mul_f32_e32 v9, v134, v9
	v_lshlrev_b32_e32 v10, 16, v38
	v_and_b32_e32 v11, 0xffff0000, v38
	v_cvt_i32_f32_e32 v4, v4
	v_cvt_i32_f32_sdwa v6, v6 dst_sel:WORD_1 dst_unused:UNUSED_PAD src0_sel:DWORD
	v_cvt_i32_f32_e32 v7, v7
	v_mul_f32_e32 v8, v134, v8
	v_rndne_f32_e32 v9, v9
	v_mul_f32_e32 v10, v134, v10
	v_mul_f32_e32 v11, v134, v11
	v_rndne_f32_e32 v8, v8
	v_cvt_i32_f32_e32 v9, v9
	v_rndne_f32_e32 v10, v10
	v_rndne_f32_e32 v11, v11
	v_cvt_i32_f32_e32 v8, v8
	v_cvt_i32_f32_sdwa v10, v10 dst_sel:WORD_1 dst_unused:UNUSED_PAD src0_sel:DWORD
	v_cvt_i32_f32_e32 v11, v11
	v_lshlrev_b32_e32 v5, 8, v5
	v_and_b32_e32 v5, 0xff00, v5
	v_and_b32_e32 v6, 0xff0000, v6
	v_perm_b32 v4, v7, v4, s81
	v_or3_b32 v4, v4, v5, v6
	v_lshlrev_b32_e32 v5, 8, v9
	v_and_b32_e32 v5, 0xff00, v5
	v_and_b32_e32 v6, 0xff0000, v10
	v_perm_b32 v7, v11, v8, s81
	v_or3_b32 v5, v7, v5, v6
	v_add_co_u32_e32 v6, vcc, s67, v2
	v_cvt_pk_bf16_f32 v43, v43, v47
	s_nop 0
	v_addc_co_u32_e32 v7, vcc, 0, v3, vcc
	global_store_dwordx2 v[6:7], v[4:5], off
	v_and_b32_e32 v5, 0xffff0000, v34
	v_cvt_pk_bf16_f32 v47, v50, v54
	v_lshlrev_b32_e32 v4, 16, v34
	v_mul_f32_e32 v5, v131, v5
	v_lshlrev_b32_e32 v6, 16, v42
	v_and_b32_e32 v7, 0xffff0000, v42
	v_cvt_pk_bf16_f32 v35, v35, v39
	v_cvt_pk_bf16_f32 v39, v58, v62
	v_mul_f32_e32 v4, v131, v4
	v_rndne_f32_e32 v5, v5
	v_mul_f32_e32 v6, v131, v6
	v_mul_f32_e32 v7, v131, v7
	v_and_b32_e32 v9, 0xffff0000, v47
	v_rndne_f32_e32 v4, v4
	v_cvt_i32_f32_e32 v5, v5
	v_rndne_f32_e32 v6, v6
	v_rndne_f32_e32 v7, v7
	v_lshlrev_b32_e32 v8, 16, v47
	v_mul_f32_e32 v9, v131, v9
	v_lshlrev_b32_e32 v10, 16, v39
	v_and_b32_e32 v11, 0xffff0000, v39
	v_cvt_i32_f32_e32 v4, v4
	v_cvt_i32_f32_sdwa v6, v6 dst_sel:WORD_1 dst_unused:UNUSED_PAD src0_sel:DWORD
	v_cvt_i32_f32_e32 v7, v7
	v_mul_f32_e32 v8, v131, v8
	v_rndne_f32_e32 v9, v9
	v_mul_f32_e32 v10, v131, v10
	v_mul_f32_e32 v11, v131, v11
	v_rndne_f32_e32 v8, v8
	v_cvt_i32_f32_e32 v9, v9
	v_rndne_f32_e32 v10, v10
	v_rndne_f32_e32 v11, v11
	v_cvt_i32_f32_e32 v8, v8
	v_cvt_i32_f32_sdwa v10, v10 dst_sel:WORD_1 dst_unused:UNUSED_PAD src0_sel:DWORD
	v_cvt_i32_f32_e32 v11, v11
	v_lshlrev_b32_e32 v5, 8, v5
	v_and_b32_e32 v5, 0xff00, v5
	v_and_b32_e32 v6, 0xff0000, v6
	v_perm_b32 v4, v7, v4, s81
	v_or3_b32 v4, v4, v5, v6
	v_lshlrev_b32_e32 v5, 8, v9
	v_and_b32_e32 v5, 0xff00, v5
	v_and_b32_e32 v6, 0xff0000, v10
	v_perm_b32 v7, v11, v8, s81
	v_or3_b32 v5, v7, v5, v6
	v_add_co_u32_e32 v6, vcc, s33, v2
	v_cvt_pk_bf16_f32 v51, v51, v55
	s_nop 0
	v_addc_co_u32_e32 v7, vcc, 0, v3, vcc
	global_store_dwordx2 v[6:7], v[4:5], off
	v_and_b32_e32 v5, 0xffff0000, v35
	v_lshlrev_b32_e32 v4, 16, v35
	v_mul_f32_e32 v5, v130, v5
	v_lshlrev_b32_e32 v6, 16, v43
	v_and_b32_e32 v7, 0xffff0000, v43
	v_cvt_pk_bf16_f32 v59, v59, v63
	v_mul_f32_e32 v4, v130, v4
	v_rndne_f32_e32 v5, v5
	v_mul_f32_e32 v6, v130, v6
	v_mul_f32_e32 v7, v130, v7
	v_and_b32_e32 v9, 0xffff0000, v51
	v_rndne_f32_e32 v4, v4
	v_cvt_i32_f32_e32 v5, v5
	v_rndne_f32_e32 v6, v6
	v_rndne_f32_e32 v7, v7
	v_lshlrev_b32_e32 v8, 16, v51
	v_mul_f32_e32 v9, v130, v9
	v_lshlrev_b32_e32 v10, 16, v59
	v_and_b32_e32 v11, 0xffff0000, v59
	v_cvt_i32_f32_e32 v4, v4
	v_cvt_i32_f32_sdwa v6, v6 dst_sel:WORD_1 dst_unused:UNUSED_PAD src0_sel:DWORD
	v_cvt_i32_f32_e32 v7, v7
	v_mul_f32_e32 v8, v130, v8
	v_rndne_f32_e32 v9, v9
	v_mul_f32_e32 v10, v130, v10
	v_mul_f32_e32 v11, v130, v11
	v_rndne_f32_e32 v8, v8
	v_cvt_i32_f32_e32 v9, v9
	v_rndne_f32_e32 v10, v10
	v_rndne_f32_e32 v11, v11
	v_cvt_i32_f32_e32 v8, v8
	v_cvt_i32_f32_sdwa v10, v10 dst_sel:WORD_1 dst_unused:UNUSED_PAD src0_sel:DWORD
	v_cvt_i32_f32_e32 v11, v11
	v_lshlrev_b32_e32 v5, 8, v5
	v_and_b32_e32 v5, 0xff00, v5
	v_and_b32_e32 v6, 0xff0000, v6
	v_perm_b32 v4, v7, v4, s81
	v_or3_b32 v4, v4, v5, v6
	v_lshlrev_b32_e32 v5, 8, v9
	v_and_b32_e32 v5, 0xff00, v5
	v_and_b32_e32 v6, 0xff0000, v10
	v_perm_b32 v7, v11, v8, s81
	v_add_co_u32_e32 v2, vcc, s44, v2
	v_cvt_pk_bf16_f32 v64, v64, v68
	v_or3_b32 v5, v7, v5, v6
	v_addc_co_u32_e32 v3, vcc, 0, v3, vcc
	v_cvt_pk_bf16_f32 v72, v72, v76
	global_store_dwordx2 v[2:3], v[4:5], off
	v_and_b32_e32 v5, 0xffff0000, v64
	v_cvt_pk_bf16_f32 v73, v73, v77
	v_cvt_pk_bf16_f32 v77, v80, v84
	v_lshlrev_b32_e32 v4, 16, v64
	v_mul_f32_e32 v5, v135, v5
	v_lshlrev_b32_e32 v6, 16, v72
	v_and_b32_e32 v7, 0xffff0000, v72
	v_cvt_pk_bf16_f32 v65, v65, v69
	v_cvt_pk_bf16_f32 v69, v88, v92
	v_mul_f32_e32 v4, v135, v4
	v_rndne_f32_e32 v5, v5
	v_mul_f32_e32 v6, v135, v6
	v_mul_f32_e32 v7, v135, v7
	v_and_b32_e32 v9, 0xffff0000, v77
	v_rndne_f32_e32 v4, v4
	v_cvt_i32_f32_e32 v5, v5
	v_rndne_f32_e32 v6, v6
	v_rndne_f32_e32 v7, v7
	v_lshlrev_b32_e32 v8, 16, v77
	v_mul_f32_e32 v9, v135, v9
	v_lshlrev_b32_e32 v10, 16, v69
	v_and_b32_e32 v11, 0xffff0000, v69
	v_cvt_i32_f32_e32 v4, v4
	v_cvt_i32_f32_sdwa v6, v6 dst_sel:WORD_1 dst_unused:UNUSED_PAD src0_sel:DWORD
	v_cvt_i32_f32_e32 v7, v7
	v_mul_f32_e32 v8, v135, v8
	v_rndne_f32_e32 v9, v9
	v_mul_f32_e32 v10, v135, v10
	v_mul_f32_e32 v11, v135, v11
	v_rndne_f32_e32 v8, v8
	v_cvt_i32_f32_e32 v9, v9
	v_rndne_f32_e32 v10, v10
	v_rndne_f32_e32 v11, v11
	v_cvt_i32_f32_e32 v8, v8
	v_cvt_i32_f32_sdwa v10, v10 dst_sel:WORD_1 dst_unused:UNUSED_PAD src0_sel:DWORD
	v_cvt_i32_f32_e32 v11, v11
	v_lshlrev_b32_e32 v5, 8, v5
	v_and_b32_e32 v5, 0xff00, v5
	v_and_b32_e32 v6, 0xff0000, v6
	v_perm_b32 v4, v7, v4, s81
	v_or3_b32 v4, v4, v5, v6
	v_lshlrev_b32_e32 v5, 8, v9
	v_and_b32_e32 v5, 0xff00, v5
	v_and_b32_e32 v6, 0xff0000, v10
	v_perm_b32 v7, v11, v8, s81
	v_lshl_add_u64 v[2:3], v[0:1], 0, s[42:43]
	v_or3_b32 v5, v7, v5, v6
	global_store_dwordx2 v[2:3], v[4:5], off
	v_and_b32_e32 v5, 0xffff0000, v65
; #define LAS __attribute__((address_space(3)))
; __device__ __forceinline__ float bflo(unsigned w) { return __uint_as_float(w << 16); }
; __device__ __forceinline__ float bfhi(unsigned w) { return __uint_as_float(w & 0xffff0000u); }
; __device__ __forceinline__ void direct_w8_block(const Ctx& c, LAS unsigned char* lds, const float* Wsrc, const int INC_, int srccol, unsigned char* dstrow, float* swdst) {
;     ...
;         for (int j = 0; j < 4; ++j) { v4u pk;
;             if (t < 4) { pk.x = held[t & 3][j][0]; pk.y = held[t & 3][j][1]; pk.z = held[t & 3][j][2]; pk.w = held[t & 3][j][3]; }
;             else pk = *(const LAS v4u*)(hl + ((t - 4) * 4 + j) * 1024);
;             int qi[8];
; #pragma unroll
;             for (int pr = 0; pr < 4; ++pr) { qi[2 * pr] = __float2int_rn(bflo(pk[pr]) * inv[j]); qi[2 * pr + 1] = __float2int_rn(bfhi(pk[pr]) * inv[j]); }
;             v2u w; w.x = (unsigned)(qi[0] & 255) | ((unsigned)(qi[1] & 255) << 8) | ((unsigned)(qi[2] & 255) << 16) | ((unsigned)(qi[3] & 255) << 24);
;             w.y = (unsigned)(qi[4] & 255) | ((unsigned)(qi[5] & 255) << 8) | ((unsigned)(qi[6] & 255) << 16) | ((unsigned)(qi[7] & 255) << 24);
;             *(v2u*)(dt + (size_t)j * DM) = w; } }
	v_cvt_pk_bf16_f32 v74, v74, v78
	v_cvt_pk_bf16_f32 v78, v81, v85
	v_lshlrev_b32_e32 v4, 16, v65
	v_mul_f32_e32 v5, v134, v5
	v_lshlrev_b32_e32 v6, 16, v73
	v_and_b32_e32 v7, 0xffff0000, v73
	v_cvt_pk_bf16_f32 v66, v66, v70
	v_cvt_pk_bf16_f32 v70, v89, v93
	v_mul_f32_e32 v4, v134, v4
	v_rndne_f32_e32 v5, v5
	v_mul_f32_e32 v6, v134, v6
	v_mul_f32_e32 v7, v134, v7
	v_and_b32_e32 v9, 0xffff0000, v78
	v_rndne_f32_e32 v4, v4
	v_cvt_i32_f32_e32 v5, v5
	v_rndne_f32_e32 v6, v6
	v_rndne_f32_e32 v7, v7
	v_lshlrev_b32_e32 v8, 16, v78
	v_mul_f32_e32 v9, v134, v9
	v_lshlrev_b32_e32 v10, 16, v70
	v_and_b32_e32 v11, 0xffff0000, v70
	v_cvt_i32_f32_e32 v4, v4
	v_cvt_i32_f32_sdwa v6, v6 dst_sel:WORD_1 dst_unused:UNUSED_PAD src0_sel:DWORD
	v_cvt_i32_f32_e32 v7, v7
	v_mul_f32_e32 v8, v134, v8
	v_rndne_f32_e32 v9, v9
	v_mul_f32_e32 v10, v134, v10
	v_mul_f32_e32 v11, v134, v11
	v_rndne_f32_e32 v8, v8
	v_cvt_i32_f32_e32 v9, v9
	v_rndne_f32_e32 v10, v10
	v_rndne_f32_e32 v11, v11
	v_cvt_i32_f32_e32 v8, v8
	v_cvt_i32_f32_sdwa v10, v10 dst_sel:WORD_1 dst_unused:UNUSED_PAD src0_sel:DWORD
	v_cvt_i32_f32_e32 v11, v11
	v_lshlrev_b32_e32 v5, 8, v5
	v_and_b32_e32 v5, 0xff00, v5
	v_and_b32_e32 v6, 0xff0000, v6
	v_perm_b32 v4, v7, v4, s81
	v_or3_b32 v4, v4, v5, v6
	v_lshlrev_b32_e32 v5, 8, v9
	v_and_b32_e32 v5, 0xff00, v5
	v_and_b32_e32 v6, 0xff0000, v10
	v_perm_b32 v7, v11, v8, s81
	v_or3_b32 v5, v7, v5, v6
	v_add_co_u32_e32 v6, vcc, s67, v2
	v_cvt_pk_bf16_f32 v75, v75, v79
	s_nop 0
	v_addc_co_u32_e32 v7, vcc, 0, v3, vcc
	global_store_dwordx2 v[6:7], v[4:5], off
	v_and_b32_e32 v5, 0xffff0000, v66
	v_cvt_pk_bf16_f32 v79, v82, v86
	v_lshlrev_b32_e32 v4, 16, v66
	v_mul_f32_e32 v5, v131, v5
	v_lshlrev_b32_e32 v6, 16, v74
	v_and_b32_e32 v7, 0xffff0000, v74
	v_cvt_pk_bf16_f32 v67, v67, v71
	v_cvt_pk_bf16_f32 v71, v90, v94
	v_mul_f32_e32 v4, v131, v4
	v_rndne_f32_e32 v5, v5
	v_mul_f32_e32 v6, v131, v6
	v_mul_f32_e32 v7, v131, v7
	v_and_b32_e32 v9, 0xffff0000, v79
	v_rndne_f32_e32 v4, v4
	v_cvt_i32_f32_e32 v5, v5
	v_rndne_f32_e32 v6, v6
	v_rndne_f32_e32 v7, v7
	v_lshlrev_b32_e32 v8, 16, v79
	v_mul_f32_e32 v9, v131, v9
	v_lshlrev_b32_e32 v10, 16, v71
	v_and_b32_e32 v11, 0xffff0000, v71
	v_cvt_i32_f32_e32 v4, v4
	v_cvt_i32_f32_sdwa v6, v6 dst_sel:WORD_1 dst_unused:UNUSED_PAD src0_sel:DWORD
	v_cvt_i32_f32_e32 v7, v7
	v_mul_f32_e32 v8, v131, v8
	v_rndne_f32_e32 v9, v9
	v_mul_f32_e32 v10, v131, v10
	v_mul_f32_e32 v11, v131, v11
	v_rndne_f32_e32 v8, v8
	v_cvt_i32_f32_e32 v9, v9
	v_rndne_f32_e32 v10, v10
	v_rndne_f32_e32 v11, v11
	v_cvt_i32_f32_e32 v8, v8
	v_cvt_i32_f32_sdwa v10, v10 dst_sel:WORD_1 dst_unused:UNUSED_PAD src0_sel:DWORD
	v_cvt_i32_f32_e32 v11, v11
	v_lshlrev_b32_e32 v5, 8, v5
	v_and_b32_e32 v5, 0xff00, v5
	v_and_b32_e32 v6, 0xff0000, v6
	v_perm_b32 v4, v7, v4, s81
	v_or3_b32 v4, v4, v5, v6
	v_lshlrev_b32_e32 v5, 8, v9
	v_and_b32_e32 v5, 0xff00, v5
	v_and_b32_e32 v6, 0xff0000, v10
	v_perm_b32 v7, v11, v8, s81
	v_or3_b32 v5, v7, v5, v6
	v_add_co_u32_e32 v6, vcc, s33, v2
	v_cvt_pk_bf16_f32 v83, v83, v87
	s_nop 0
	v_addc_co_u32_e32 v7, vcc, 0, v3, vcc
	global_store_dwordx2 v[6:7], v[4:5], off
	v_and_b32_e32 v5, 0xffff0000, v67
	v_lshlrev_b32_e32 v4, 16, v67
	v_mul_f32_e32 v5, v130, v5
	v_lshlrev_b32_e32 v6, 16, v75
	v_and_b32_e32 v7, 0xffff0000, v75
	v_cvt_pk_bf16_f32 v91, v91, v95
	v_mul_f32_e32 v4, v130, v4
	v_rndne_f32_e32 v5, v5
	v_mul_f32_e32 v6, v130, v6
	v_mul_f32_e32 v7, v130, v7
	v_and_b32_e32 v9, 0xffff0000, v83
	v_rndne_f32_e32 v4, v4
	v_cvt_i32_f32_e32 v5, v5
	v_rndne_f32_e32 v6, v6
	v_rndne_f32_e32 v7, v7
	v_lshlrev_b32_e32 v8, 16, v83
	v_mul_f32_e32 v9, v130, v9
	v_lshlrev_b32_e32 v10, 16, v91
	v_and_b32_e32 v11, 0xffff0000, v91
	v_cvt_i32_f32_e32 v4, v4
	v_cvt_i32_f32_sdwa v6, v6 dst_sel:WORD_1 dst_unused:UNUSED_PAD src0_sel:DWORD
	v_cvt_i32_f32_e32 v7, v7
	v_mul_f32_e32 v8, v130, v8
	v_rndne_f32_e32 v9, v9
	v_mul_f32_e32 v10, v130, v10
	v_mul_f32_e32 v11, v130, v11
	v_rndne_f32_e32 v8, v8
	v_cvt_i32_f32_e32 v9, v9
	v_rndne_f32_e32 v10, v10
	v_rndne_f32_e32 v11, v11
	v_cvt_i32_f32_e32 v8, v8
	v_cvt_i32_f32_sdwa v10, v10 dst_sel:WORD_1 dst_unused:UNUSED_PAD src0_sel:DWORD
	v_cvt_i32_f32_e32 v11, v11
	v_lshlrev_b32_e32 v5, 8, v5
	v_and_b32_e32 v5, 0xff00, v5
	v_and_b32_e32 v6, 0xff0000, v6
	v_perm_b32 v4, v7, v4, s81
	v_or3_b32 v4, v4, v5, v6
	v_lshlrev_b32_e32 v5, 8, v9
	v_and_b32_e32 v5, 0xff00, v5
	v_and_b32_e32 v6, 0xff0000, v10
	v_perm_b32 v7, v11, v8, s81
	v_add_co_u32_e32 v2, vcc, s44, v2
	v_cvt_pk_bf16_f32 v98, v98, v102
	v_or3_b32 v5, v7, v5, v6
	v_addc_co_u32_e32 v3, vcc, 0, v3, vcc
	v_cvt_pk_bf16_f32 v106, v106, v110
	global_store_dwordx2 v[2:3], v[4:5], off
	v_and_b32_e32 v5, 0xffff0000, v98
	v_cvt_pk_bf16_f32 v107, v107, v111
	v_cvt_pk_bf16_f32 v111, v114, v118
	v_lshlrev_b32_e32 v4, 16, v98
	v_mul_f32_e32 v5, v135, v5
	v_lshlrev_b32_e32 v6, 16, v106
	v_and_b32_e32 v7, 0xffff0000, v106
	v_cvt_pk_bf16_f32 v99, v99, v103
	v_cvt_pk_bf16_f32 v103, v122, v126
	v_mul_f32_e32 v4, v135, v4
	v_rndne_f32_e32 v5, v5
	v_mul_f32_e32 v6, v135, v6
	v_mul_f32_e32 v7, v135, v7
	v_and_b32_e32 v9, 0xffff0000, v111
	v_rndne_f32_e32 v4, v4
	v_cvt_i32_f32_e32 v5, v5
	v_rndne_f32_e32 v6, v6
	v_rndne_f32_e32 v7, v7
	v_lshlrev_b32_e32 v8, 16, v111
	v_mul_f32_e32 v9, v135, v9
	v_lshlrev_b32_e32 v10, 16, v103
	v_and_b32_e32 v11, 0xffff0000, v103
	v_cvt_i32_f32_e32 v4, v4
	v_cvt_i32_f32_sdwa v6, v6 dst_sel:WORD_1 dst_unused:UNUSED_PAD src0_sel:DWORD
	v_cvt_i32_f32_e32 v7, v7
	v_mul_f32_e32 v8, v135, v8
	v_rndne_f32_e32 v9, v9
	v_mul_f32_e32 v10, v135, v10
	v_mul_f32_e32 v11, v135, v11
	v_rndne_f32_e32 v8, v8
	v_cvt_i32_f32_e32 v9, v9
	v_rndne_f32_e32 v10, v10
	v_rndne_f32_e32 v11, v11
; #define LAS __attribute__((address_space(3)))
; __device__ __forceinline__ float bflo(unsigned w) { return __uint_as_float(w << 16); }
; __device__ __forceinline__ float bfhi(unsigned w) { return __uint_as_float(w & 0xffff0000u); }
; __device__ __forceinline__ void direct_w8_block(const Ctx& c, LAS unsigned char* lds, const float* Wsrc, const int INC_, int srccol, unsigned char* dstrow, float* swdst) {
;     ...
;         for (int j = 0; j < 4; ++j) { v4u pk;
;             if (t < 4) { pk.x = held[t & 3][j][0]; pk.y = held[t & 3][j][1]; pk.z = held[t & 3][j][2]; pk.w = held[t & 3][j][3]; }
;             else pk = *(const LAS v4u*)(hl + ((t - 4) * 4 + j) * 1024);
;             int qi[8];
; #pragma unroll
;             for (int pr = 0; pr < 4; ++pr) { qi[2 * pr] = __float2int_rn(bflo(pk[pr]) * inv[j]); qi[2 * pr + 1] = __float2int_rn(bfhi(pk[pr]) * inv[j]); }
;             v2u w; w.x = (unsigned)(qi[0] & 255) | ((unsigned)(qi[1] & 255) << 8) | ((unsigned)(qi[2] & 255) << 16) | ((unsigned)(qi[3] & 255) << 24);
;             w.y = (unsigned)(qi[4] & 255) | ((unsigned)(qi[5] & 255) << 8) | ((unsigned)(qi[6] & 255) << 16) | ((unsigned)(qi[7] & 255) << 24);
;             *(v2u*)(dt + (size_t)j * DM) = w; } }
	v_cvt_i32_f32_e32 v8, v8
	v_cvt_i32_f32_sdwa v10, v10 dst_sel:WORD_1 dst_unused:UNUSED_PAD src0_sel:DWORD
	v_cvt_i32_f32_e32 v11, v11
	v_lshlrev_b32_e32 v5, 8, v5
	v_and_b32_e32 v5, 0xff00, v5
	v_and_b32_e32 v6, 0xff0000, v6
	v_perm_b32 v4, v7, v4, s81
	v_or3_b32 v4, v4, v5, v6
	v_lshlrev_b32_e32 v5, 8, v9
	s_mov_b64 s[2:3], 0xc0
	v_and_b32_e32 v5, 0xff00, v5
	v_and_b32_e32 v6, 0xff0000, v10
	v_perm_b32 v7, v11, v8, s81
	v_lshl_add_u64 v[2:3], v[0:1], 0, s[2:3]
	v_or3_b32 v5, v7, v5, v6
	global_store_dwordx2 v[2:3], v[4:5], off
	v_and_b32_e32 v5, 0xffff0000, v99
	v_cvt_pk_bf16_f32 v108, v108, v112
	v_cvt_pk_bf16_f32 v112, v115, v119
	v_lshlrev_b32_e32 v4, 16, v99
	v_mul_f32_e32 v5, v134, v5
	v_lshlrev_b32_e32 v6, 16, v107
	v_and_b32_e32 v7, 0xffff0000, v107
	v_cvt_pk_bf16_f32 v100, v100, v104
	v_cvt_pk_bf16_f32 v104, v123, v127
	v_mul_f32_e32 v4, v134, v4
	v_rndne_f32_e32 v5, v5
	v_mul_f32_e32 v6, v134, v6
	v_mul_f32_e32 v7, v134, v7
	v_and_b32_e32 v9, 0xffff0000, v112
	v_rndne_f32_e32 v4, v4
	v_cvt_i32_f32_e32 v5, v5
	v_rndne_f32_e32 v6, v6
	v_rndne_f32_e32 v7, v7
	v_lshlrev_b32_e32 v8, 16, v112
	v_mul_f32_e32 v9, v134, v9
	v_lshlrev_b32_e32 v10, 16, v104
	v_and_b32_e32 v11, 0xffff0000, v104
	v_cvt_i32_f32_e32 v4, v4
	v_cvt_i32_f32_sdwa v6, v6 dst_sel:WORD_1 dst_unused:UNUSED_PAD src0_sel:DWORD
	v_cvt_i32_f32_e32 v7, v7
	v_mul_f32_e32 v8, v134, v8
	v_rndne_f32_e32 v9, v9
	v_mul_f32_e32 v10, v134, v10
	v_mul_f32_e32 v11, v134, v11
	v_rndne_f32_e32 v8, v8
	v_cvt_i32_f32_e32 v9, v9
	v_rndne_f32_e32 v10, v10
	v_rndne_f32_e32 v11, v11
	v_cvt_i32_f32_e32 v8, v8
	v_cvt_i32_f32_sdwa v10, v10 dst_sel:WORD_1 dst_unused:UNUSED_PAD src0_sel:DWORD
	v_cvt_i32_f32_e32 v11, v11
	v_lshlrev_b32_e32 v5, 8, v5
	v_and_b32_e32 v5, 0xff00, v5
	v_and_b32_e32 v6, 0xff0000, v6
	v_perm_b32 v4, v7, v4, s81
	v_or3_b32 v4, v4, v5, v6
	v_lshlrev_b32_e32 v5, 8, v9
	v_and_b32_e32 v5, 0xff00, v5
	v_and_b32_e32 v6, 0xff0000, v10
	v_perm_b32 v7, v11, v8, s81
	v_or3_b32 v5, v7, v5, v6
	v_add_co_u32_e32 v6, vcc, s67, v2
	v_cvt_pk_bf16_f32 v109, v109, v113
	s_nop 0
	v_addc_co_u32_e32 v7, vcc, 0, v3, vcc
	global_store_dwordx2 v[6:7], v[4:5], off
	v_and_b32_e32 v5, 0xffff0000, v100
	v_cvt_pk_bf16_f32 v113, v116, v120
	v_lshlrev_b32_e32 v4, 16, v100
	v_mul_f32_e32 v5, v131, v5
	v_lshlrev_b32_e32 v6, 16, v108
	v_and_b32_e32 v7, 0xffff0000, v108
	v_cvt_pk_bf16_f32 v101, v101, v105
	v_cvt_pk_bf16_f32 v105, v124, v128
	v_mul_f32_e32 v4, v131, v4
	v_rndne_f32_e32 v5, v5
	v_mul_f32_e32 v6, v131, v6
	v_mul_f32_e32 v7, v131, v7
	v_and_b32_e32 v9, 0xffff0000, v113
	v_rndne_f32_e32 v4, v4
	v_cvt_i32_f32_e32 v5, v5
	v_rndne_f32_e32 v6, v6
	v_rndne_f32_e32 v7, v7
	v_lshlrev_b32_e32 v8, 16, v113
	v_mul_f32_e32 v9, v131, v9
	v_lshlrev_b32_e32 v10, 16, v105
	v_and_b32_e32 v11, 0xffff0000, v105
	v_cvt_i32_f32_e32 v4, v4
	v_cvt_i32_f32_sdwa v6, v6 dst_sel:WORD_1 dst_unused:UNUSED_PAD src0_sel:DWORD
	v_cvt_i32_f32_e32 v7, v7
	v_mul_f32_e32 v8, v131, v8
	v_rndne_f32_e32 v9, v9
	v_mul_f32_e32 v10, v131, v10
	v_mul_f32_e32 v11, v131, v11
	v_rndne_f32_e32 v8, v8
	v_cvt_i32_f32_e32 v9, v9
	v_rndne_f32_e32 v10, v10
	v_rndne_f32_e32 v11, v11
	v_cvt_i32_f32_e32 v8, v8
	v_cvt_i32_f32_sdwa v10, v10 dst_sel:WORD_1 dst_unused:UNUSED_PAD src0_sel:DWORD
	v_cvt_i32_f32_e32 v11, v11
	v_lshlrev_b32_e32 v5, 8, v5
	v_and_b32_e32 v5, 0xff00, v5
	v_and_b32_e32 v6, 0xff0000, v6
	v_perm_b32 v4, v7, v4, s81
	v_or3_b32 v4, v4, v5, v6
	v_lshlrev_b32_e32 v5, 8, v9
	v_and_b32_e32 v5, 0xff00, v5
	v_and_b32_e32 v6, 0xff0000, v10
	v_perm_b32 v7, v11, v8, s81
	v_or3_b32 v5, v7, v5, v6
	v_add_co_u32_e32 v6, vcc, s33, v2
	v_cvt_pk_bf16_f32 v117, v117, v121
	s_nop 0
	v_addc_co_u32_e32 v7, vcc, 0, v3, vcc
	global_store_dwordx2 v[6:7], v[4:5], off
	v_and_b32_e32 v5, 0xffff0000, v101
	v_lshlrev_b32_e32 v4, 16, v101
	v_mul_f32_e32 v5, v130, v5
	v_lshlrev_b32_e32 v6, 16, v109
	v_and_b32_e32 v7, 0xffff0000, v109
	v_cvt_pk_bf16_f32 v125, v125, v129
	v_mul_f32_e32 v4, v130, v4
	v_rndne_f32_e32 v5, v5
	v_mul_f32_e32 v6, v130, v6
	v_mul_f32_e32 v7, v130, v7
	v_and_b32_e32 v9, 0xffff0000, v117
	v_rndne_f32_e32 v4, v4
	v_cvt_i32_f32_e32 v5, v5
	v_rndne_f32_e32 v6, v6
	v_rndne_f32_e32 v7, v7
	v_lshlrev_b32_e32 v8, 16, v117
	v_mul_f32_e32 v9, v130, v9
	v_lshlrev_b32_e32 v10, 16, v125
	v_and_b32_e32 v11, 0xffff0000, v125
	v_cvt_i32_f32_e32 v4, v4
	v_cvt_i32_f32_sdwa v6, v6 dst_sel:WORD_1 dst_unused:UNUSED_PAD src0_sel:DWORD
	v_cvt_i32_f32_e32 v7, v7
	v_mul_f32_e32 v8, v130, v8
	v_rndne_f32_e32 v9, v9
	v_mul_f32_e32 v10, v130, v10
	v_mul_f32_e32 v11, v130, v11
	v_rndne_f32_e32 v8, v8
	v_cvt_i32_f32_e32 v9, v9
	v_rndne_f32_e32 v10, v10
	v_rndne_f32_e32 v11, v11
	v_cvt_i32_f32_e32 v8, v8
	v_cvt_i32_f32_sdwa v10, v10 dst_sel:WORD_1 dst_unused:UNUSED_PAD src0_sel:DWORD
	v_cvt_i32_f32_e32 v11, v11
	v_lshlrev_b32_e32 v5, 8, v5
	v_and_b32_e32 v5, 0xff00, v5
	v_and_b32_e32 v6, 0xff0000, v6
	v_perm_b32 v4, v7, v4, s81
	v_or3_b32 v4, v4, v5, v6
	v_lshlrev_b32_e32 v5, 8, v9
	v_and_b32_e32 v5, 0xff00, v5
	v_and_b32_e32 v6, 0xff0000, v10
	v_perm_b32 v7, v11, v8, s81
	v_add_co_u32_e32 v2, vcc, s44, v2
	s_mov_b64 s[2:3], 0x100
	v_or3_b32 v5, v7, v5, v6
	v_addc_co_u32_e32 v3, vcc, 0, v3, vcc
	v_lshl_add_u64 v[6:7], v[0:1], 0, s[2:3]
	global_store_dwordx2 v[2:3], v[4:5], off
	ds_read_b128 v[2:5], v96
	s_mov_b64 s[2:3], 0x140
	s_add_i32 s1, s1, 64
	s_addk_i32 s10, 0x800
	s_cmp_gt_i32 s1, 63
	s_waitcnt lgkmcnt(0)
; #define LAS __attribute__((address_space(3)))
; __device__ __forceinline__ float bflo(unsigned w) { return __uint_as_float(w << 16); }
; __device__ __forceinline__ float bfhi(unsigned w) { return __uint_as_float(w & 0xffff0000u); }
; __device__ __forceinline__ void direct_w8_block(const Ctx& c, LAS unsigned char* lds, const float* Wsrc, const int INC_, int srccol, unsigned char* dstrow, float* swdst) {
;     ...
;         for (int j = 0; j < 4; ++j) { v4u pk;
;             if (t < 4) { pk.x = held[t & 3][j][0]; pk.y = held[t & 3][j][1]; pk.z = held[t & 3][j][2]; pk.w = held[t & 3][j][3]; }
;             else pk = *(const LAS v4u*)(hl + ((t - 4) * 4 + j) * 1024);
;             int qi[8];
; #pragma unroll
;             for (int pr = 0; pr < 4; ++pr) { qi[2 * pr] = __float2int_rn(bflo(pk[pr]) * inv[j]); qi[2 * pr + 1] = __float2int_rn(bfhi(pk[pr]) * inv[j]); }
;             v2u w; w.x = (unsigned)(qi[0] & 255) | ((unsigned)(qi[1] & 255) << 8) | ((unsigned)(qi[2] & 255) << 16) | ((unsigned)(qi[3] & 255) << 24);
;             w.y = (unsigned)(qi[4] & 255) | ((unsigned)(qi[5] & 255) << 8) | ((unsigned)(qi[6] & 255) << 16) | ((unsigned)(qi[7] & 255) << 24);
;             *(v2u*)(dt + (size_t)j * DM) = w; } }
	v_lshlrev_b32_e32 v8, 16, v2
	v_and_b32_e32 v2, 0xffff0000, v2
	v_mul_f32_e32 v2, v135, v2
	v_lshlrev_b32_e32 v9, 16, v3
	v_and_b32_e32 v3, 0xffff0000, v3
	v_mul_f32_e32 v8, v135, v8
	v_rndne_f32_e32 v2, v2
	v_mul_f32_e32 v9, v135, v9
	v_mul_f32_e32 v3, v135, v3
	v_lshlrev_b32_e32 v10, 16, v4
	v_and_b32_e32 v4, 0xffff0000, v4
	v_rndne_f32_e32 v8, v8
	v_cvt_i32_f32_e32 v2, v2
	v_rndne_f32_e32 v9, v9
	v_rndne_f32_e32 v3, v3
	v_mul_f32_e32 v4, v135, v4
	v_lshlrev_b32_e32 v11, 16, v5
	v_and_b32_e32 v5, 0xffff0000, v5
	v_cvt_i32_f32_e32 v8, v8
	v_cvt_i32_f32_sdwa v9, v9 dst_sel:WORD_1 dst_unused:UNUSED_PAD src0_sel:DWORD
	v_cvt_i32_f32_e32 v3, v3
	v_mul_f32_e32 v10, v135, v10
	v_rndne_f32_e32 v4, v4
	v_mul_f32_e32 v11, v135, v11
	v_mul_f32_e32 v5, v135, v5
	v_rndne_f32_e32 v10, v10
	v_cvt_i32_f32_e32 v4, v4
	v_rndne_f32_e32 v11, v11
	v_rndne_f32_e32 v5, v5
	v_cvt_i32_f32_e32 v10, v10
	v_cvt_i32_f32_sdwa v11, v11 dst_sel:WORD_1 dst_unused:UNUSED_PAD src0_sel:DWORD
	v_cvt_i32_f32_e32 v5, v5
	v_lshlrev_b32_e32 v2, 8, v2
	v_and_b32_e32 v2, 0xff00, v2
	v_and_b32_e32 v9, 0xff0000, v9
	v_perm_b32 v3, v3, v8, s81
	v_or3_b32 v2, v3, v2, v9
	v_lshlrev_b32_e32 v3, 8, v4
	v_and_b32_e32 v3, 0xff00, v3
	v_and_b32_e32 v4, 0xff0000, v11
	v_perm_b32 v5, v5, v10, s81
	v_or3_b32 v3, v5, v3, v4
	global_store_dwordx2 v[6:7], v[2:3], off
	ds_read_b128 v[2:5], v96 offset:1024
	s_waitcnt lgkmcnt(0)
	v_lshlrev_b32_e32 v8, 16, v2
	v_and_b32_e32 v2, 0xffff0000, v2
	v_mul_f32_e32 v2, v134, v2
	v_lshlrev_b32_e32 v9, 16, v3
	v_and_b32_e32 v3, 0xffff0000, v3
	v_mul_f32_e32 v8, v134, v8
	v_rndne_f32_e32 v2, v2
	v_mul_f32_e32 v9, v134, v9
	v_mul_f32_e32 v3, v134, v3
	v_lshlrev_b32_e32 v10, 16, v4
	v_and_b32_e32 v4, 0xffff0000, v4
	v_rndne_f32_e32 v8, v8
	v_cvt_i32_f32_e32 v2, v2
	v_rndne_f32_e32 v9, v9
	v_rndne_f32_e32 v3, v3
	v_mul_f32_e32 v4, v134, v4
	v_lshlrev_b32_e32 v11, 16, v5
	v_and_b32_e32 v5, 0xffff0000, v5
	v_cvt_i32_f32_e32 v8, v8
	v_cvt_i32_f32_sdwa v9, v9 dst_sel:WORD_1 dst_unused:UNUSED_PAD src0_sel:DWORD
	v_cvt_i32_f32_e32 v3, v3
	v_mul_f32_e32 v10, v134, v10
	v_rndne_f32_e32 v4, v4
	v_mul_f32_e32 v11, v134, v11
	v_mul_f32_e32 v5, v134, v5
	v_rndne_f32_e32 v10, v10
	v_cvt_i32_f32_e32 v4, v4
	v_rndne_f32_e32 v11, v11
	v_rndne_f32_e32 v5, v5
	v_cvt_i32_f32_e32 v10, v10
	v_cvt_i32_f32_sdwa v11, v11 dst_sel:WORD_1 dst_unused:UNUSED_PAD src0_sel:DWORD
	v_cvt_i32_f32_e32 v5, v5
	v_lshlrev_b32_e32 v2, 8, v2
	v_and_b32_e32 v2, 0xff00, v2
	v_and_b32_e32 v9, 0xff0000, v9
	v_perm_b32 v3, v3, v8, s81
	v_or3_b32 v2, v3, v2, v9
	v_lshlrev_b32_e32 v3, 8, v4
	v_and_b32_e32 v3, 0xff00, v3
	v_and_b32_e32 v4, 0xff0000, v11
	v_perm_b32 v5, v5, v10, s81
	v_or3_b32 v3, v5, v3, v4
	v_add_co_u32_e32 v4, vcc, s67, v6
	s_nop 1
	v_addc_co_u32_e32 v5, vcc, 0, v7, vcc
	global_store_dwordx2 v[4:5], v[2:3], off
	ds_read_b128 v[2:5], v96 offset:2048
	s_waitcnt lgkmcnt(0)
	v_lshlrev_b32_e32 v8, 16, v2
	v_and_b32_e32 v2, 0xffff0000, v2
	v_mul_f32_e32 v2, v131, v2
	v_lshlrev_b32_e32 v9, 16, v3
	v_and_b32_e32 v3, 0xffff0000, v3
	v_mul_f32_e32 v8, v131, v8
	v_rndne_f32_e32 v2, v2
	v_mul_f32_e32 v9, v131, v9
	v_mul_f32_e32 v3, v131, v3
	v_lshlrev_b32_e32 v10, 16, v4
	v_and_b32_e32 v4, 0xffff0000, v4
	v_rndne_f32_e32 v8, v8
	v_cvt_i32_f32_e32 v2, v2
	v_rndne_f32_e32 v9, v9
	v_rndne_f32_e32 v3, v3
	v_mul_f32_e32 v4, v131, v4
	v_lshlrev_b32_e32 v11, 16, v5
	v_and_b32_e32 v5, 0xffff0000, v5
	v_cvt_i32_f32_e32 v8, v8
	v_cvt_i32_f32_sdwa v9, v9 dst_sel:WORD_1 dst_unused:UNUSED_PAD src0_sel:DWORD
	v_cvt_i32_f32_e32 v3, v3
	v_mul_f32_e32 v10, v131, v10
	v_rndne_f32_e32 v4, v4
	v_mul_f32_e32 v11, v131, v11
	v_mul_f32_e32 v5, v131, v5
	v_rndne_f32_e32 v10, v10
	v_cvt_i32_f32_e32 v4, v4
	v_rndne_f32_e32 v11, v11
	v_rndne_f32_e32 v5, v5
	v_cvt_i32_f32_e32 v10, v10
	v_cvt_i32_f32_sdwa v11, v11 dst_sel:WORD_1 dst_unused:UNUSED_PAD src0_sel:DWORD
	v_cvt_i32_f32_e32 v5, v5
	v_lshlrev_b32_e32 v2, 8, v2
	v_and_b32_e32 v2, 0xff00, v2
	v_and_b32_e32 v9, 0xff0000, v9
	v_perm_b32 v3, v3, v8, s81
	v_or3_b32 v2, v3, v2, v9
	v_lshlrev_b32_e32 v3, 8, v4
	v_and_b32_e32 v3, 0xff00, v3
	v_and_b32_e32 v4, 0xff0000, v11
	v_perm_b32 v5, v5, v10, s81
	v_or3_b32 v3, v5, v3, v4
	v_add_co_u32_e32 v4, vcc, s33, v6
	s_nop 1
	v_addc_co_u32_e32 v5, vcc, 0, v7, vcc
	global_store_dwordx2 v[4:5], v[2:3], off
	ds_read_b128 v[2:5], v96 offset:3072
	s_waitcnt lgkmcnt(0)
	v_lshlrev_b32_e32 v8, 16, v2
	v_and_b32_e32 v2, 0xffff0000, v2
	v_mul_f32_e32 v2, v130, v2
	v_lshlrev_b32_e32 v9, 16, v3
	v_and_b32_e32 v3, 0xffff0000, v3
	v_mul_f32_e32 v8, v130, v8
	v_rndne_f32_e32 v2, v2
	v_mul_f32_e32 v9, v130, v9
	v_mul_f32_e32 v3, v130, v3
	v_lshlrev_b32_e32 v10, 16, v4
	v_and_b32_e32 v4, 0xffff0000, v4
	v_rndne_f32_e32 v8, v8
	v_cvt_i32_f32_e32 v2, v2
	v_rndne_f32_e32 v9, v9
	v_rndne_f32_e32 v3, v3
	v_mul_f32_e32 v4, v130, v4
	v_lshlrev_b32_e32 v11, 16, v5
	v_and_b32_e32 v5, 0xffff0000, v5
	v_cvt_i32_f32_e32 v8, v8
	v_cvt_i32_f32_sdwa v9, v9 dst_sel:WORD_1 dst_unused:UNUSED_PAD src0_sel:DWORD
	v_cvt_i32_f32_e32 v3, v3
	v_mul_f32_e32 v10, v130, v10
	v_rndne_f32_e32 v4, v4
	v_mul_f32_e32 v11, v130, v11
	v_mul_f32_e32 v5, v130, v5
	v_rndne_f32_e32 v10, v10
	v_cvt_i32_f32_e32 v4, v4
	v_rndne_f32_e32 v11, v11
	v_rndne_f32_e32 v5, v5
	v_cvt_i32_f32_e32 v10, v10
	v_cvt_i32_f32_sdwa v11, v11 dst_sel:WORD_1 dst_unused:UNUSED_PAD src0_sel:DWORD
	v_cvt_i32_f32_e32 v5, v5
	v_lshlrev_b32_e32 v2, 8, v2
	v_and_b32_e32 v2, 0xff00, v2
	v_and_b32_e32 v9, 0xff0000, v9
	v_perm_b32 v3, v3, v8, s81
	v_or3_b32 v2, v3, v2, v9
	v_lshlrev_b32_e32 v3, 8, v4
	v_and_b32_e32 v3, 0xff00, v3
	v_and_b32_e32 v4, 0xff0000, v11
	v_perm_b32 v5, v5, v10, s81
	v_or3_b32 v3, v5, v3, v4
	v_add_co_u32_e32 v4, vcc, s44, v6
	s_nop 1
	v_addc_co_u32_e32 v5, vcc, 0, v7, vcc
	v_lshl_add_u64 v[6:7], v[0:1], 0, s[2:3]
	global_store_dwordx2 v[4:5], v[2:3], off
	ds_read_b128 v[2:5], v96 offset:4096
	s_mov_b64 s[2:3], 0x180
	s_waitcnt lgkmcnt(0)
; #define LAS __attribute__((address_space(3)))
; __device__ __forceinline__ float bflo(unsigned w) { return __uint_as_float(w << 16); }
; __device__ __forceinline__ float bfhi(unsigned w) { return __uint_as_float(w & 0xffff0000u); }
; __device__ __forceinline__ void direct_w8_block(const Ctx& c, LAS unsigned char* lds, const float* Wsrc, const int INC_, int srccol, unsigned char* dstrow, float* swdst) {
;     ...
;         for (int j = 0; j < 4; ++j) { v4u pk;
;             if (t < 4) { pk.x = held[t & 3][j][0]; pk.y = held[t & 3][j][1]; pk.z = held[t & 3][j][2]; pk.w = held[t & 3][j][3]; }
;             else pk = *(const LAS v4u*)(hl + ((t - 4) * 4 + j) * 1024);
;             int qi[8];
; #pragma unroll
;             for (int pr = 0; pr < 4; ++pr) { qi[2 * pr] = __float2int_rn(bflo(pk[pr]) * inv[j]); qi[2 * pr + 1] = __float2int_rn(bfhi(pk[pr]) * inv[j]); }
;             v2u w; w.x = (unsigned)(qi[0] & 255) | ((unsigned)(qi[1] & 255) << 8) | ((unsigned)(qi[2] & 255) << 16) | ((unsigned)(qi[3] & 255) << 24);
;             w.y = (unsigned)(qi[4] & 255) | ((unsigned)(qi[5] & 255) << 8) | ((unsigned)(qi[6] & 255) << 16) | ((unsigned)(qi[7] & 255) << 24);
;             *(v2u*)(dt + (size_t)j * DM) = w; } }
	v_lshlrev_b32_e32 v8, 16, v2
	v_and_b32_e32 v2, 0xffff0000, v2
	v_mul_f32_e32 v2, v135, v2
	v_lshlrev_b32_e32 v9, 16, v3
	v_and_b32_e32 v3, 0xffff0000, v3
	v_mul_f32_e32 v8, v135, v8
	v_rndne_f32_e32 v2, v2
	v_mul_f32_e32 v9, v135, v9
	v_mul_f32_e32 v3, v135, v3
	v_lshlrev_b32_e32 v10, 16, v4
	v_and_b32_e32 v4, 0xffff0000, v4
	v_rndne_f32_e32 v8, v8
	v_cvt_i32_f32_e32 v2, v2
	v_rndne_f32_e32 v9, v9
	v_rndne_f32_e32 v3, v3
	v_mul_f32_e32 v4, v135, v4
	v_lshlrev_b32_e32 v11, 16, v5
	v_and_b32_e32 v5, 0xffff0000, v5
	v_cvt_i32_f32_e32 v8, v8
	v_cvt_i32_f32_sdwa v9, v9 dst_sel:WORD_1 dst_unused:UNUSED_PAD src0_sel:DWORD
	v_cvt_i32_f32_e32 v3, v3
	v_mul_f32_e32 v10, v135, v10
	v_rndne_f32_e32 v4, v4
	v_mul_f32_e32 v11, v135, v11
	v_mul_f32_e32 v5, v135, v5
	v_rndne_f32_e32 v10, v10
	v_cvt_i32_f32_e32 v4, v4
	v_rndne_f32_e32 v11, v11
	v_rndne_f32_e32 v5, v5
	v_cvt_i32_f32_e32 v10, v10
	v_cvt_i32_f32_sdwa v11, v11 dst_sel:WORD_1 dst_unused:UNUSED_PAD src0_sel:DWORD
	v_cvt_i32_f32_e32 v5, v5
	v_lshlrev_b32_e32 v2, 8, v2
	v_and_b32_e32 v2, 0xff00, v2
	v_and_b32_e32 v9, 0xff0000, v9
	v_perm_b32 v3, v3, v8, s81
	v_or3_b32 v2, v3, v2, v9
	v_lshlrev_b32_e32 v3, 8, v4
	v_and_b32_e32 v3, 0xff00, v3
	v_and_b32_e32 v4, 0xff0000, v11
	v_perm_b32 v5, v5, v10, s81
	v_or3_b32 v3, v5, v3, v4
	global_store_dwordx2 v[6:7], v[2:3], off
	ds_read_b128 v[2:5], v96 offset:5120
	s_waitcnt lgkmcnt(0)
	v_lshlrev_b32_e32 v8, 16, v2
	v_and_b32_e32 v2, 0xffff0000, v2
	v_mul_f32_e32 v2, v134, v2
	v_lshlrev_b32_e32 v9, 16, v3
	v_and_b32_e32 v3, 0xffff0000, v3
	v_mul_f32_e32 v8, v134, v8
	v_rndne_f32_e32 v2, v2
	v_mul_f32_e32 v9, v134, v9
	v_mul_f32_e32 v3, v134, v3
	v_lshlrev_b32_e32 v10, 16, v4
	v_and_b32_e32 v4, 0xffff0000, v4
	v_rndne_f32_e32 v8, v8
	v_cvt_i32_f32_e32 v2, v2
	v_rndne_f32_e32 v9, v9
	v_rndne_f32_e32 v3, v3
	v_mul_f32_e32 v4, v134, v4
	v_lshlrev_b32_e32 v11, 16, v5
	v_and_b32_e32 v5, 0xffff0000, v5
	v_cvt_i32_f32_e32 v8, v8
	v_cvt_i32_f32_sdwa v9, v9 dst_sel:WORD_1 dst_unused:UNUSED_PAD src0_sel:DWORD
	v_cvt_i32_f32_e32 v3, v3
	v_mul_f32_e32 v10, v134, v10
	v_rndne_f32_e32 v4, v4
	v_mul_f32_e32 v11, v134, v11
	v_mul_f32_e32 v5, v134, v5
	v_rndne_f32_e32 v10, v10
	v_cvt_i32_f32_e32 v4, v4
	v_rndne_f32_e32 v11, v11
	v_rndne_f32_e32 v5, v5
	v_cvt_i32_f32_e32 v10, v10
	v_cvt_i32_f32_sdwa v11, v11 dst_sel:WORD_1 dst_unused:UNUSED_PAD src0_sel:DWORD
	v_cvt_i32_f32_e32 v5, v5
	v_lshlrev_b32_e32 v2, 8, v2
	v_and_b32_e32 v2, 0xff00, v2
	v_and_b32_e32 v9, 0xff0000, v9
	v_perm_b32 v3, v3, v8, s81
	v_or3_b32 v2, v3, v2, v9
	v_lshlrev_b32_e32 v3, 8, v4
	v_and_b32_e32 v3, 0xff00, v3
	v_and_b32_e32 v4, 0xff0000, v11
	v_perm_b32 v5, v5, v10, s81
	v_or3_b32 v3, v5, v3, v4
	v_add_co_u32_e32 v4, vcc, s67, v6
	s_nop 1
	v_addc_co_u32_e32 v5, vcc, 0, v7, vcc
	global_store_dwordx2 v[4:5], v[2:3], off
	ds_read_b128 v[2:5], v96 offset:6144
	s_waitcnt lgkmcnt(0)
	v_lshlrev_b32_e32 v8, 16, v2
	v_and_b32_e32 v2, 0xffff0000, v2
	v_mul_f32_e32 v2, v131, v2
	v_lshlrev_b32_e32 v9, 16, v3
	v_and_b32_e32 v3, 0xffff0000, v3
	v_mul_f32_e32 v8, v131, v8
	v_rndne_f32_e32 v2, v2
	v_mul_f32_e32 v9, v131, v9
	v_mul_f32_e32 v3, v131, v3
	v_lshlrev_b32_e32 v10, 16, v4
	v_and_b32_e32 v4, 0xffff0000, v4
	v_rndne_f32_e32 v8, v8
	v_cvt_i32_f32_e32 v2, v2
	v_rndne_f32_e32 v9, v9
	v_rndne_f32_e32 v3, v3
	v_mul_f32_e32 v4, v131, v4
	v_lshlrev_b32_e32 v11, 16, v5
	v_and_b32_e32 v5, 0xffff0000, v5
	v_cvt_i32_f32_e32 v8, v8
	v_cvt_i32_f32_sdwa v9, v9 dst_sel:WORD_1 dst_unused:UNUSED_PAD src0_sel:DWORD
	v_cvt_i32_f32_e32 v3, v3
	v_mul_f32_e32 v10, v131, v10
	v_rndne_f32_e32 v4, v4
	v_mul_f32_e32 v11, v131, v11
	v_mul_f32_e32 v5, v131, v5
	v_rndne_f32_e32 v10, v10
	v_cvt_i32_f32_e32 v4, v4
	v_rndne_f32_e32 v11, v11
	v_rndne_f32_e32 v5, v5
	v_cvt_i32_f32_e32 v10, v10
	v_cvt_i32_f32_sdwa v11, v11 dst_sel:WORD_1 dst_unused:UNUSED_PAD src0_sel:DWORD
	v_cvt_i32_f32_e32 v5, v5
	v_lshlrev_b32_e32 v2, 8, v2
	v_and_b32_e32 v2, 0xff00, v2
	v_and_b32_e32 v9, 0xff0000, v9
	v_perm_b32 v3, v3, v8, s81
	v_or3_b32 v2, v3, v2, v9
	v_lshlrev_b32_e32 v3, 8, v4
	v_and_b32_e32 v3, 0xff00, v3
	v_and_b32_e32 v4, 0xff0000, v11
	v_perm_b32 v5, v5, v10, s81
	v_or3_b32 v3, v5, v3, v4
	v_add_co_u32_e32 v4, vcc, s33, v6
	s_nop 1
	v_addc_co_u32_e32 v5, vcc, 0, v7, vcc
	global_store_dwordx2 v[4:5], v[2:3], off
	ds_read_b128 v[2:5], v96 offset:7168
	s_waitcnt lgkmcnt(0)
	v_lshlrev_b32_e32 v8, 16, v2
	v_and_b32_e32 v2, 0xffff0000, v2
	v_mul_f32_e32 v2, v130, v2
	v_lshlrev_b32_e32 v9, 16, v3
	v_and_b32_e32 v3, 0xffff0000, v3
	v_mul_f32_e32 v8, v130, v8
	v_rndne_f32_e32 v2, v2
	v_mul_f32_e32 v9, v130, v9
	v_mul_f32_e32 v3, v130, v3
	v_lshlrev_b32_e32 v10, 16, v4
	v_and_b32_e32 v4, 0xffff0000, v4
	v_rndne_f32_e32 v8, v8
	v_cvt_i32_f32_e32 v2, v2
	v_rndne_f32_e32 v9, v9
	v_rndne_f32_e32 v3, v3
	v_mul_f32_e32 v4, v130, v4
	v_lshlrev_b32_e32 v11, 16, v5
	v_and_b32_e32 v5, 0xffff0000, v5
	v_cvt_i32_f32_e32 v8, v8
	v_cvt_i32_f32_sdwa v9, v9 dst_sel:WORD_1 dst_unused:UNUSED_PAD src0_sel:DWORD
	v_cvt_i32_f32_e32 v3, v3
	v_mul_f32_e32 v10, v130, v10
	v_rndne_f32_e32 v4, v4
	v_mul_f32_e32 v11, v130, v11
	v_mul_f32_e32 v5, v130, v5
	v_rndne_f32_e32 v10, v10
	v_cvt_i32_f32_e32 v4, v4
	v_rndne_f32_e32 v11, v11
	v_rndne_f32_e32 v5, v5
	v_cvt_i32_f32_e32 v10, v10
	v_cvt_i32_f32_sdwa v11, v11 dst_sel:WORD_1 dst_unused:UNUSED_PAD src0_sel:DWORD
	v_cvt_i32_f32_e32 v5, v5
	v_lshlrev_b32_e32 v2, 8, v2
	v_and_b32_e32 v2, 0xff00, v2
	v_and_b32_e32 v9, 0xff0000, v9
	v_perm_b32 v3, v3, v8, s81
	v_or3_b32 v2, v3, v2, v9
	v_lshlrev_b32_e32 v3, 8, v4
	v_and_b32_e32 v3, 0xff00, v3
	v_and_b32_e32 v4, 0xff0000, v11
	v_perm_b32 v5, v5, v10, s81
	v_or3_b32 v3, v5, v3, v4
	v_add_co_u32_e32 v4, vcc, s44, v6
	s_nop 1
	v_addc_co_u32_e32 v5, vcc, 0, v7, vcc
	v_lshl_add_u64 v[6:7], v[0:1], 0, s[2:3]
	global_store_dwordx2 v[4:5], v[2:3], off
	ds_read_b128 v[2:5], v96 offset:8192
	s_mov_b64 s[2:3], 0x1c0
	s_waitcnt lgkmcnt(0)
; #define LAS __attribute__((address_space(3)))
; __device__ __forceinline__ float bflo(unsigned w) { return __uint_as_float(w << 16); }
; __device__ __forceinline__ float bfhi(unsigned w) { return __uint_as_float(w & 0xffff0000u); }
; __device__ __forceinline__ void direct_w8_block(const Ctx& c, LAS unsigned char* lds, const float* Wsrc, const int INC_, int srccol, unsigned char* dstrow, float* swdst) {
;     ...
;         for (int j = 0; j < 4; ++j) { v4u pk;
;             if (t < 4) { pk.x = held[t & 3][j][0]; pk.y = held[t & 3][j][1]; pk.z = held[t & 3][j][2]; pk.w = held[t & 3][j][3]; }
;             else pk = *(const LAS v4u*)(hl + ((t - 4) * 4 + j) * 1024);
;             int qi[8];
; #pragma unroll
;             for (int pr = 0; pr < 4; ++pr) { qi[2 * pr] = __float2int_rn(bflo(pk[pr]) * inv[j]); qi[2 * pr + 1] = __float2int_rn(bfhi(pk[pr]) * inv[j]); }
;             v2u w; w.x = (unsigned)(qi[0] & 255) | ((unsigned)(qi[1] & 255) << 8) | ((unsigned)(qi[2] & 255) << 16) | ((unsigned)(qi[3] & 255) << 24);
;             w.y = (unsigned)(qi[4] & 255) | ((unsigned)(qi[5] & 255) << 8) | ((unsigned)(qi[6] & 255) << 16) | ((unsigned)(qi[7] & 255) << 24);
;             *(v2u*)(dt + (size_t)j * DM) = w; } }
	v_lshlrev_b32_e32 v8, 16, v2
	v_and_b32_e32 v2, 0xffff0000, v2
	v_mul_f32_e32 v2, v135, v2
	v_lshlrev_b32_e32 v9, 16, v3
	v_and_b32_e32 v3, 0xffff0000, v3
	v_mul_f32_e32 v8, v135, v8
	v_rndne_f32_e32 v2, v2
	v_mul_f32_e32 v9, v135, v9
	v_mul_f32_e32 v3, v135, v3
	v_lshlrev_b32_e32 v10, 16, v4
	v_and_b32_e32 v4, 0xffff0000, v4
	v_rndne_f32_e32 v8, v8
	v_cvt_i32_f32_e32 v2, v2
	v_rndne_f32_e32 v9, v9
	v_rndne_f32_e32 v3, v3
	v_mul_f32_e32 v4, v135, v4
	v_lshlrev_b32_e32 v11, 16, v5
	v_and_b32_e32 v5, 0xffff0000, v5
	v_cvt_i32_f32_e32 v8, v8
	v_cvt_i32_f32_sdwa v9, v9 dst_sel:WORD_1 dst_unused:UNUSED_PAD src0_sel:DWORD
	v_cvt_i32_f32_e32 v3, v3
	v_mul_f32_e32 v10, v135, v10
	v_rndne_f32_e32 v4, v4
	v_mul_f32_e32 v11, v135, v11
	v_mul_f32_e32 v5, v135, v5
	v_rndne_f32_e32 v10, v10
	v_cvt_i32_f32_e32 v4, v4
	v_rndne_f32_e32 v11, v11
	v_rndne_f32_e32 v5, v5
	v_cvt_i32_f32_e32 v10, v10
	v_cvt_i32_f32_sdwa v11, v11 dst_sel:WORD_1 dst_unused:UNUSED_PAD src0_sel:DWORD
	v_cvt_i32_f32_e32 v5, v5
	v_lshlrev_b32_e32 v2, 8, v2
	v_and_b32_e32 v2, 0xff00, v2
	v_and_b32_e32 v9, 0xff0000, v9
	v_perm_b32 v3, v3, v8, s81
	v_or3_b32 v2, v3, v2, v9
	v_lshlrev_b32_e32 v3, 8, v4
	v_and_b32_e32 v3, 0xff00, v3
	v_and_b32_e32 v4, 0xff0000, v11
	v_perm_b32 v5, v5, v10, s81
	v_or3_b32 v3, v5, v3, v4
	global_store_dwordx2 v[6:7], v[2:3], off
	ds_read_b128 v[2:5], v96 offset:9216
	s_waitcnt lgkmcnt(0)
	v_lshlrev_b32_e32 v8, 16, v2
	v_and_b32_e32 v2, 0xffff0000, v2
	v_mul_f32_e32 v2, v134, v2
	v_lshlrev_b32_e32 v9, 16, v3
	v_and_b32_e32 v3, 0xffff0000, v3
	v_mul_f32_e32 v8, v134, v8
	v_rndne_f32_e32 v2, v2
	v_mul_f32_e32 v9, v134, v9
	v_mul_f32_e32 v3, v134, v3
	v_lshlrev_b32_e32 v10, 16, v4
	v_and_b32_e32 v4, 0xffff0000, v4
	v_rndne_f32_e32 v8, v8
	v_cvt_i32_f32_e32 v2, v2
	v_rndne_f32_e32 v9, v9
	v_rndne_f32_e32 v3, v3
	v_mul_f32_e32 v4, v134, v4
	v_lshlrev_b32_e32 v11, 16, v5
	v_and_b32_e32 v5, 0xffff0000, v5
	v_cvt_i32_f32_e32 v8, v8
	v_cvt_i32_f32_sdwa v9, v9 dst_sel:WORD_1 dst_unused:UNUSED_PAD src0_sel:DWORD
	v_cvt_i32_f32_e32 v3, v3
	v_mul_f32_e32 v10, v134, v10
	v_rndne_f32_e32 v4, v4
	v_mul_f32_e32 v11, v134, v11
	v_mul_f32_e32 v5, v134, v5
	v_rndne_f32_e32 v10, v10
	v_cvt_i32_f32_e32 v4, v4
	v_rndne_f32_e32 v11, v11
	v_rndne_f32_e32 v5, v5
	v_cvt_i32_f32_e32 v10, v10
	v_cvt_i32_f32_sdwa v11, v11 dst_sel:WORD_1 dst_unused:UNUSED_PAD src0_sel:DWORD
	v_cvt_i32_f32_e32 v5, v5
	v_lshlrev_b32_e32 v2, 8, v2
	v_and_b32_e32 v2, 0xff00, v2
	v_and_b32_e32 v9, 0xff0000, v9
	v_perm_b32 v3, v3, v8, s81
	v_or3_b32 v2, v3, v2, v9
	v_lshlrev_b32_e32 v3, 8, v4
	v_and_b32_e32 v3, 0xff00, v3
	v_and_b32_e32 v4, 0xff0000, v11
	v_perm_b32 v5, v5, v10, s81
	v_or3_b32 v3, v5, v3, v4
	v_add_co_u32_e32 v4, vcc, s67, v6
	s_nop 1
	v_addc_co_u32_e32 v5, vcc, 0, v7, vcc
	global_store_dwordx2 v[4:5], v[2:3], off
	ds_read_b128 v[2:5], v96 offset:10240
	s_waitcnt lgkmcnt(0)
	v_lshlrev_b32_e32 v8, 16, v2
	v_and_b32_e32 v2, 0xffff0000, v2
	v_mul_f32_e32 v2, v131, v2
	v_lshlrev_b32_e32 v9, 16, v3
	v_and_b32_e32 v3, 0xffff0000, v3
	v_mul_f32_e32 v8, v131, v8
	v_rndne_f32_e32 v2, v2
	v_mul_f32_e32 v9, v131, v9
	v_mul_f32_e32 v3, v131, v3
	v_lshlrev_b32_e32 v10, 16, v4
	v_and_b32_e32 v4, 0xffff0000, v4
	v_rndne_f32_e32 v8, v8
	v_cvt_i32_f32_e32 v2, v2
	v_rndne_f32_e32 v9, v9
	v_rndne_f32_e32 v3, v3
	v_mul_f32_e32 v4, v131, v4
	v_lshlrev_b32_e32 v11, 16, v5
	v_and_b32_e32 v5, 0xffff0000, v5
	v_cvt_i32_f32_e32 v8, v8
	v_cvt_i32_f32_sdwa v9, v9 dst_sel:WORD_1 dst_unused:UNUSED_PAD src0_sel:DWORD
	v_cvt_i32_f32_e32 v3, v3
	v_mul_f32_e32 v10, v131, v10
	v_rndne_f32_e32 v4, v4
	v_mul_f32_e32 v11, v131, v11
	v_mul_f32_e32 v5, v131, v5
	v_rndne_f32_e32 v10, v10
	v_cvt_i32_f32_e32 v4, v4
	v_rndne_f32_e32 v11, v11
	v_rndne_f32_e32 v5, v5
	v_cvt_i32_f32_e32 v10, v10
	v_cvt_i32_f32_sdwa v11, v11 dst_sel:WORD_1 dst_unused:UNUSED_PAD src0_sel:DWORD
	v_cvt_i32_f32_e32 v5, v5
	v_lshlrev_b32_e32 v2, 8, v2
	v_and_b32_e32 v2, 0xff00, v2
	v_and_b32_e32 v9, 0xff0000, v9
	v_perm_b32 v3, v3, v8, s81
	v_or3_b32 v2, v3, v2, v9
	v_lshlrev_b32_e32 v3, 8, v4
	v_and_b32_e32 v3, 0xff00, v3
	v_and_b32_e32 v4, 0xff0000, v11
	v_perm_b32 v5, v5, v10, s81
	v_or3_b32 v3, v5, v3, v4
	v_add_co_u32_e32 v4, vcc, s33, v6
	s_nop 1
	v_addc_co_u32_e32 v5, vcc, 0, v7, vcc
	global_store_dwordx2 v[4:5], v[2:3], off
	ds_read_b128 v[2:5], v96 offset:11264
	s_waitcnt lgkmcnt(0)
	v_lshlrev_b32_e32 v8, 16, v2
	v_and_b32_e32 v2, 0xffff0000, v2
	v_mul_f32_e32 v2, v130, v2
	v_lshlrev_b32_e32 v9, 16, v3
	v_and_b32_e32 v3, 0xffff0000, v3
	v_mul_f32_e32 v8, v130, v8
	v_rndne_f32_e32 v2, v2
	v_mul_f32_e32 v9, v130, v9
	v_mul_f32_e32 v3, v130, v3
	v_lshlrev_b32_e32 v10, 16, v4
	v_and_b32_e32 v4, 0xffff0000, v4
	v_rndne_f32_e32 v8, v8
	v_cvt_i32_f32_e32 v2, v2
	v_rndne_f32_e32 v9, v9
	v_rndne_f32_e32 v3, v3
	v_mul_f32_e32 v4, v130, v4
	v_lshlrev_b32_e32 v11, 16, v5
	v_and_b32_e32 v5, 0xffff0000, v5
	v_cvt_i32_f32_e32 v8, v8
	v_cvt_i32_f32_sdwa v9, v9 dst_sel:WORD_1 dst_unused:UNUSED_PAD src0_sel:DWORD
	v_cvt_i32_f32_e32 v3, v3
	v_mul_f32_e32 v10, v130, v10
	v_rndne_f32_e32 v4, v4
	v_mul_f32_e32 v11, v130, v11
	v_mul_f32_e32 v5, v130, v5
	v_rndne_f32_e32 v10, v10
	v_cvt_i32_f32_e32 v4, v4
	v_rndne_f32_e32 v11, v11
	v_rndne_f32_e32 v5, v5
	v_cvt_i32_f32_e32 v10, v10
	v_cvt_i32_f32_sdwa v11, v11 dst_sel:WORD_1 dst_unused:UNUSED_PAD src0_sel:DWORD
	v_cvt_i32_f32_e32 v5, v5
	v_lshlrev_b32_e32 v2, 8, v2
	v_and_b32_e32 v2, 0xff00, v2
	v_and_b32_e32 v9, 0xff0000, v9
	v_perm_b32 v3, v3, v8, s81
	v_or3_b32 v2, v3, v2, v9
	v_lshlrev_b32_e32 v3, 8, v4
	v_and_b32_e32 v3, 0xff00, v3
	v_and_b32_e32 v4, 0xff0000, v11
	v_perm_b32 v5, v5, v10, s81
	v_or3_b32 v3, v5, v3, v4
	v_add_co_u32_e32 v4, vcc, s44, v6
	s_nop 1
	v_addc_co_u32_e32 v5, vcc, 0, v7, vcc
	global_store_dwordx2 v[4:5], v[2:3], off
	v_lshl_add_u64 v[4:5], v[0:1], 0, s[2:3]
	ds_read_b128 v[0:3], v96 offset:12288
	s_waitcnt lgkmcnt(0)
; #define LAS __attribute__((address_space(3)))
; __device__ __forceinline__ float bflo(unsigned w) { return __uint_as_float(w << 16); }
; __device__ __forceinline__ float bfhi(unsigned w) { return __uint_as_float(w & 0xffff0000u); }
; __device__ __forceinline__ void direct_w8_block(const Ctx& c, LAS unsigned char* lds, const float* Wsrc, const int INC_, int srccol, unsigned char* dstrow, float* swdst) {
;     ...
;         for (int j = 0; j < 4; ++j) { v4u pk;
;             if (t < 4) { pk.x = held[t & 3][j][0]; pk.y = held[t & 3][j][1]; pk.z = held[t & 3][j][2]; pk.w = held[t & 3][j][3]; }
;             else pk = *(const LAS v4u*)(hl + ((t - 4) * 4 + j) * 1024);
;             int qi[8];
; #pragma unroll
;             for (int pr = 0; pr < 4; ++pr) { qi[2 * pr] = __float2int_rn(bflo(pk[pr]) * inv[j]); qi[2 * pr + 1] = __float2int_rn(bfhi(pk[pr]) * inv[j]); }
;             v2u w; w.x = (unsigned)(qi[0] & 255) | ((unsigned)(qi[1] & 255) << 8) | ((unsigned)(qi[2] & 255) << 16) | ((unsigned)(qi[3] & 255) << 24);
;             w.y = (unsigned)(qi[4] & 255) | ((unsigned)(qi[5] & 255) << 8) | ((unsigned)(qi[6] & 255) << 16) | ((unsigned)(qi[7] & 255) << 24);
;             *(v2u*)(dt + (size_t)j * DM) = w; } }
	v_lshlrev_b32_e32 v6, 16, v0
	v_and_b32_e32 v0, 0xffff0000, v0
	v_mul_f32_e32 v0, v135, v0
	v_lshlrev_b32_e32 v7, 16, v1
	v_and_b32_e32 v1, 0xffff0000, v1
	v_mul_f32_e32 v6, v135, v6
	v_rndne_f32_e32 v0, v0
	v_mul_f32_e32 v7, v135, v7
	v_mul_f32_e32 v1, v135, v1
	v_lshlrev_b32_e32 v8, 16, v2
	v_and_b32_e32 v2, 0xffff0000, v2
	v_rndne_f32_e32 v6, v6
	v_cvt_i32_f32_e32 v0, v0
	v_rndne_f32_e32 v7, v7
	v_rndne_f32_e32 v1, v1
	v_mul_f32_e32 v2, v135, v2
	v_lshlrev_b32_e32 v9, 16, v3
	v_and_b32_e32 v3, 0xffff0000, v3
	v_cvt_i32_f32_e32 v6, v6
	v_cvt_i32_f32_sdwa v7, v7 dst_sel:WORD_1 dst_unused:UNUSED_PAD src0_sel:DWORD
	v_cvt_i32_f32_e32 v1, v1
	v_mul_f32_e32 v8, v135, v8
	v_rndne_f32_e32 v2, v2
	v_mul_f32_e32 v9, v135, v9
	v_mul_f32_e32 v3, v135, v3
	v_rndne_f32_e32 v8, v8
	v_cvt_i32_f32_e32 v2, v2
	v_rndne_f32_e32 v9, v9
	v_rndne_f32_e32 v3, v3
	v_cvt_i32_f32_e32 v8, v8
	v_cvt_i32_f32_sdwa v9, v9 dst_sel:WORD_1 dst_unused:UNUSED_PAD src0_sel:DWORD
	v_cvt_i32_f32_e32 v3, v3
	v_lshlrev_b32_e32 v0, 8, v0
	v_and_b32_e32 v0, 0xff00, v0
	v_and_b32_e32 v7, 0xff0000, v7
	v_perm_b32 v1, v1, v6, s81
	v_or3_b32 v0, v1, v0, v7
	v_lshlrev_b32_e32 v1, 8, v2
	v_and_b32_e32 v1, 0xff00, v1
	v_and_b32_e32 v2, 0xff0000, v9
	v_perm_b32 v3, v3, v8, s81
	v_or3_b32 v1, v3, v1, v2
	global_store_dwordx2 v[4:5], v[0:1], off
	ds_read_b128 v[0:3], v96 offset:13312
	s_waitcnt lgkmcnt(0)
	v_lshlrev_b32_e32 v6, 16, v0
	v_and_b32_e32 v0, 0xffff0000, v0
	v_mul_f32_e32 v0, v134, v0
	v_lshlrev_b32_e32 v7, 16, v1
	v_and_b32_e32 v1, 0xffff0000, v1
	v_mul_f32_e32 v6, v134, v6
	v_rndne_f32_e32 v0, v0
	v_mul_f32_e32 v7, v134, v7
	v_mul_f32_e32 v1, v134, v1
	v_lshlrev_b32_e32 v8, 16, v2
	v_and_b32_e32 v2, 0xffff0000, v2
	v_rndne_f32_e32 v6, v6
	v_cvt_i32_f32_e32 v0, v0
	v_rndne_f32_e32 v7, v7
	v_rndne_f32_e32 v1, v1
	v_mul_f32_e32 v2, v134, v2
	v_lshlrev_b32_e32 v9, 16, v3
	v_and_b32_e32 v3, 0xffff0000, v3
	v_cvt_i32_f32_e32 v6, v6
	v_cvt_i32_f32_sdwa v7, v7 dst_sel:WORD_1 dst_unused:UNUSED_PAD src0_sel:DWORD
	v_cvt_i32_f32_e32 v1, v1
	v_mul_f32_e32 v8, v134, v8
	v_rndne_f32_e32 v2, v2
	v_mul_f32_e32 v9, v134, v9
	v_mul_f32_e32 v3, v134, v3
	v_rndne_f32_e32 v8, v8
	v_cvt_i32_f32_e32 v2, v2
	v_rndne_f32_e32 v9, v9
	v_rndne_f32_e32 v3, v3
	v_cvt_i32_f32_e32 v8, v8
	v_cvt_i32_f32_sdwa v9, v9 dst_sel:WORD_1 dst_unused:UNUSED_PAD src0_sel:DWORD
	v_cvt_i32_f32_e32 v3, v3
	v_lshlrev_b32_e32 v0, 8, v0
	v_and_b32_e32 v0, 0xff00, v0
	v_and_b32_e32 v7, 0xff0000, v7
	v_perm_b32 v1, v1, v6, s81
	v_or3_b32 v0, v1, v0, v7
	v_lshlrev_b32_e32 v1, 8, v2
	v_and_b32_e32 v1, 0xff00, v1
	v_and_b32_e32 v2, 0xff0000, v9
	v_perm_b32 v3, v3, v8, s81
	v_or3_b32 v1, v3, v1, v2
	v_add_co_u32_e32 v2, vcc, s67, v4
	s_nop 1
	v_addc_co_u32_e32 v3, vcc, 0, v5, vcc
	global_store_dwordx2 v[2:3], v[0:1], off
	ds_read_b128 v[0:3], v96 offset:14336
	s_waitcnt lgkmcnt(0)
	v_lshlrev_b32_e32 v6, 16, v0
	v_and_b32_e32 v0, 0xffff0000, v0
	v_mul_f32_e32 v0, v131, v0
	v_lshlrev_b32_e32 v7, 16, v1
	v_and_b32_e32 v1, 0xffff0000, v1
	v_mul_f32_e32 v6, v131, v6
	v_rndne_f32_e32 v0, v0
	v_mul_f32_e32 v7, v131, v7
	v_mul_f32_e32 v1, v131, v1
	v_lshlrev_b32_e32 v8, 16, v2
	v_and_b32_e32 v2, 0xffff0000, v2
	v_rndne_f32_e32 v6, v6
	v_cvt_i32_f32_e32 v0, v0
	v_rndne_f32_e32 v7, v7
	v_rndne_f32_e32 v1, v1
	v_mul_f32_e32 v2, v131, v2
	v_lshlrev_b32_e32 v9, 16, v3
	v_and_b32_e32 v3, 0xffff0000, v3
	v_cvt_i32_f32_e32 v6, v6
	v_cvt_i32_f32_sdwa v7, v7 dst_sel:WORD_1 dst_unused:UNUSED_PAD src0_sel:DWORD
	v_cvt_i32_f32_e32 v1, v1
	v_mul_f32_e32 v8, v131, v8
	v_rndne_f32_e32 v2, v2
	v_mul_f32_e32 v9, v131, v9
	v_mul_f32_e32 v3, v131, v3
	v_rndne_f32_e32 v8, v8
	v_cvt_i32_f32_e32 v2, v2
	v_rndne_f32_e32 v9, v9
	v_rndne_f32_e32 v3, v3
	v_cvt_i32_f32_e32 v8, v8
	v_cvt_i32_f32_sdwa v9, v9 dst_sel:WORD_1 dst_unused:UNUSED_PAD src0_sel:DWORD
	v_cvt_i32_f32_e32 v3, v3
	v_lshlrev_b32_e32 v0, 8, v0
	v_and_b32_e32 v0, 0xff00, v0
	v_and_b32_e32 v7, 0xff0000, v7
	v_perm_b32 v1, v1, v6, s81
	v_or3_b32 v0, v1, v0, v7
	v_lshlrev_b32_e32 v1, 8, v2
	v_and_b32_e32 v1, 0xff00, v1
	v_and_b32_e32 v2, 0xff0000, v9
	v_perm_b32 v3, v3, v8, s81
	v_or3_b32 v1, v3, v1, v2
	v_add_co_u32_e32 v2, vcc, s33, v4
	s_nop 1
	v_addc_co_u32_e32 v3, vcc, 0, v5, vcc
	global_store_dwordx2 v[2:3], v[0:1], off
	ds_read_b128 v[0:3], v96 offset:15360
	s_waitcnt lgkmcnt(0)
	v_lshlrev_b32_e32 v6, 16, v0
	v_and_b32_e32 v0, 0xffff0000, v0
	v_mul_f32_e32 v0, v130, v0
	v_lshlrev_b32_e32 v7, 16, v1
	v_and_b32_e32 v1, 0xffff0000, v1
	v_mul_f32_e32 v6, v130, v6
	v_rndne_f32_e32 v0, v0
	v_mul_f32_e32 v7, v130, v7
	v_mul_f32_e32 v1, v130, v1
	v_lshlrev_b32_e32 v8, 16, v2
	v_and_b32_e32 v2, 0xffff0000, v2
	v_rndne_f32_e32 v6, v6
	v_cvt_i32_f32_e32 v0, v0
	v_rndne_f32_e32 v7, v7
	v_rndne_f32_e32 v1, v1
	v_mul_f32_e32 v2, v130, v2
	v_lshlrev_b32_e32 v9, 16, v3
	v_and_b32_e32 v3, 0xffff0000, v3
	v_cvt_i32_f32_e32 v6, v6
	v_cvt_i32_f32_sdwa v7, v7 dst_sel:WORD_1 dst_unused:UNUSED_PAD src0_sel:DWORD
	v_cvt_i32_f32_e32 v1, v1
	v_mul_f32_e32 v8, v130, v8
	v_rndne_f32_e32 v2, v2
	v_mul_f32_e32 v9, v130, v9
	v_mul_f32_e32 v3, v130, v3
	v_rndne_f32_e32 v8, v8
	v_cvt_i32_f32_e32 v2, v2
	v_rndne_f32_e32 v9, v9
	v_rndne_f32_e32 v3, v3
	v_cvt_i32_f32_e32 v8, v8
	v_cvt_i32_f32_sdwa v9, v9 dst_sel:WORD_1 dst_unused:UNUSED_PAD src0_sel:DWORD
	v_cvt_i32_f32_e32 v3, v3
	v_lshlrev_b32_e32 v0, 8, v0
	v_and_b32_e32 v0, 0xff00, v0
	v_and_b32_e32 v7, 0xff0000, v7
	v_perm_b32 v1, v1, v6, s81
	v_or3_b32 v0, v1, v0, v7
	v_lshlrev_b32_e32 v1, 8, v2
	v_and_b32_e32 v1, 0xff00, v1
	v_and_b32_e32 v2, 0xff0000, v9
	v_perm_b32 v3, v3, v8, s81
	v_or3_b32 v1, v3, v1, v2
	v_add_co_u32_e32 v2, vcc, 0x3000, v4
	s_nop 1
	v_addc_co_u32_e32 v3, vcc, 0, v5, vcc
	global_store_dwordx2 v[2:3], v[0:1], off
	s_cbranch_scc1 .LBB0_457
; #define LAS __attribute__((address_space(3)))
; __device__ __forceinline__ unsigned pk2(float lo, float hi) { return pg8::cvt_pk_bf16(lo, hi); }
; __device__ __forceinline__ void direct_w8_block(const Ctx& c, LAS unsigned char* lds, const float* Wsrc, const int INC_, int srccol, unsigned char* dstrow, float* swdst) {
;     ...
;     for (int t = 0; t < 8; ++t) { f32x4 v[8]; const float* Wt = W + (size_t)(t * 64) * INC_; asm volatile("" : "+v"(Wt));
; #pragma unroll
;         for (int e = 0; e < 8; ++e) v[e] = __builtin_nontemporal_load((const f32x4*)(Wt + (size_t)e * INC_));
; #pragma unroll
;         for (int j = 0; j < 4; ++j) {
; #pragma unroll
;             for (int e = 0; e < 8; ++e) mx[j] = fmaxf(mx[j], fabsf(v[e][j]));
;             v4u pk; pk.x = pk2(v[0][j], v[1][j]); pk.y = pk2(v[2][j], v[3][j]); pk.z = pk2(v[4][j], v[5][j]); pk.w = pk2(v[6][j], v[7][j]);
;             if (t < 4) { held[t & 3][j][0] = pk.x; held[t & 3][j][1] = pk.y; held[t & 3][j][2] = pk.z; held[t & 3][j][3] = pk.w; }
;             else *(LAS v4u*)(hl + ((t - 4) * 4 + j) * 1024) = pk; }
;         if ((t & 3) == 3) { asm volatile("" ::: "memory"); __builtin_amdgcn_sched_barrier(0); } }
.LBB0_453:
	s_ashr_i32 s11, s10, 31
	v_lshl_add_u64 v[130:131], s[10:11], 2, v[162:163]
	v_mov_b64_e32 v[24:25], v[130:131]
	s_mov_b64 s[2:3], 0x600000
	v_add_co_u32_e32 v4, vcc, 0x18000, v24
	v_lshl_add_u64 v[56:57], v[130:131], 0, s[2:3]
	s_nop 0
	v_addc_co_u32_e32 v5, vcc, 0, v25, vcc
	v_add_co_u32_e32 v8, vcc, 0x30000, v24
	global_load_dwordx4 v[0:3], v[24:25], off nt
	s_nop 0
	global_load_dwordx4 v[4:7], v[4:5], off nt
	v_addc_co_u32_e32 v9, vcc, 0, v25, vcc
	v_add_co_u32_e32 v12, vcc, 0x48000, v24
	s_mov_b32 s2, 0x78000
	s_nop 0
	v_addc_co_u32_e32 v13, vcc, 0, v25, vcc
	v_add_co_u32_e32 v16, vcc, 0x60000, v24
	global_load_dwordx4 v[8:11], v[8:9], off nt
	s_nop 0
	global_load_dwordx4 v[12:15], v[12:13], off nt
	v_addc_co_u32_e32 v17, vcc, 0, v25, vcc
	v_add_co_u32_e32 v20, vcc, 0x78000, v24
	s_mov_b32 s3, 0xa8000
	s_nop 0
	v_addc_co_u32_e32 v21, vcc, 0, v25, vcc
	v_add_co_u32_e32 v26, vcc, 0x90000, v24
	global_load_dwordx4 v[16:19], v[16:17], off nt
	s_nop 0
	global_load_dwordx4 v[20:23], v[20:21], off nt
	v_addc_co_u32_e32 v27, vcc, 0, v25, vcc
	v_add_co_u32_e32 v28, vcc, 0xa8000, v24
	s_mov_b64 s[8:9], 0xc00000
	s_nop 0
	v_addc_co_u32_e32 v29, vcc, 0, v25, vcc
	global_load_dwordx4 v[24:27], v[26:27], off nt
	s_nop 0
	global_load_dwordx4 v[28:31], v[28:29], off nt
	v_lshl_add_u64 v[88:89], v[130:131], 0, s[8:9]
	v_add_co_u32_e32 v36, vcc, s61, v56
	s_mov_b64 s[8:9], 0x1200000
	s_nop 0
	v_addc_co_u32_e32 v37, vcc, 0, v57, vcc
	v_add_co_u32_e32 v40, vcc, s92, v56
	global_load_dwordx4 v[32:35], v[56:57], off nt
	s_nop 0
	global_load_dwordx4 v[36:39], v[36:37], off nt
	v_addc_co_u32_e32 v41, vcc, 0, v57, vcc
	v_add_co_u32_e32 v44, vcc, s0, v56
	v_lshl_add_u64 v[122:123], v[130:131], 0, s[8:9]
	s_nop 0
	v_addc_co_u32_e32 v45, vcc, 0, v57, vcc
	v_add_co_u32_e32 v48, vcc, s94, v56
	global_load_dwordx4 v[40:43], v[40:41], off nt
	s_nop 0
	global_load_dwordx4 v[44:47], v[44:45], off nt
	v_addc_co_u32_e32 v49, vcc, 0, v57, vcc
	v_add_co_u32_e32 v52, vcc, s2, v56
	s_waitcnt vmcnt(10) lgkmcnt(0)
	v_max3_f32 v132, |v0|, 0, |v4|
	v_addc_co_u32_e32 v53, vcc, 0, v57, vcc
	v_add_co_u32_e32 v58, vcc, s95, v56
	global_load_dwordx4 v[48:51], v[48:49], off nt
	s_nop 0
	global_load_dwordx4 v[52:55], v[52:53], off nt
	v_addc_co_u32_e32 v59, vcc, 0, v57, vcc
	v_add_co_u32_e32 v60, vcc, s3, v56
	s_waitcnt vmcnt(10)
	v_max3_f32 v132, v132, |v8|, |v12|
	s_nop 0
	v_addc_co_u32_e32 v61, vcc, 0, v57, vcc
	global_load_dwordx4 v[56:59], v[58:59], off nt
	s_nop 0
	global_load_dwordx4 v[60:63], v[60:61], off nt
	v_max3_f32 v133, |v1|, 0, |v5|
	v_add_co_u32_e32 v68, vcc, s61, v88
	v_max3_f32 v133, v133, |v9|, |v13|
	s_nop 0
	v_addc_co_u32_e32 v69, vcc, 0, v89, vcc
	v_add_co_u32_e32 v72, vcc, s92, v88
	global_load_dwordx4 v[64:67], v[88:89], off nt
	s_nop 0
	global_load_dwordx4 v[68:71], v[68:69], off nt
	v_addc_co_u32_e32 v73, vcc, 0, v89, vcc
	v_add_co_u32_e32 v76, vcc, s0, v88
	s_waitcnt vmcnt(12)
	v_max3_f32 v132, v132, |v16|, |v20|
	s_nop 0
	v_addc_co_u32_e32 v77, vcc, 0, v89, vcc
	v_add_co_u32_e32 v80, vcc, s94, v88
	global_load_dwordx4 v[72:75], v[72:73], off nt
	s_nop 0
	global_load_dwordx4 v[76:79], v[76:77], off nt
	v_addc_co_u32_e32 v81, vcc, 0, v89, vcc
	v_add_co_u32_e32 v84, vcc, s2, v88
	s_waitcnt vmcnt(12)
	v_max3_f32 v132, v132, |v24|, |v28|
	s_nop 0
	v_addc_co_u32_e32 v85, vcc, 0, v89, vcc
	v_add_co_u32_e32 v90, vcc, s95, v88
	global_load_dwordx4 v[80:83], v[80:81], off nt
	s_nop 0
	global_load_dwordx4 v[84:87], v[84:85], off nt
	v_addc_co_u32_e32 v91, vcc, 0, v89, vcc
	v_add_co_u32_e32 v92, vcc, s3, v88
	s_waitcnt vmcnt(12)
	v_max3_f32 v132, v132, |v32|, |v36|
	s_nop 0
	v_addc_co_u32_e32 v93, vcc, 0, v89, vcc
	global_load_dwordx4 v[88:91], v[90:91], off nt
	s_nop 0
	global_load_dwordx4 v[92:95], v[92:93], off nt
	s_waitcnt vmcnt(12)
	v_max3_f32 v133, v133, |v17|, |v21|
	v_add_co_u32_e32 v102, vcc, s61, v122
	v_max3_f32 v132, v132, |v40|, |v44|
	s_nop 0
	v_addc_co_u32_e32 v103, vcc, 0, v123, vcc
	v_add_co_u32_e32 v106, vcc, s92, v122
	global_load_dwordx4 v[98:101], v[122:123], off nt
	s_nop 0
	global_load_dwordx4 v[102:105], v[102:103], off nt
	v_addc_co_u32_e32 v107, vcc, 0, v123, vcc
	v_add_co_u32_e32 v110, vcc, s0, v122
	v_max3_f32 v133, v133, |v25|, |v29|
	s_nop 0
	v_addc_co_u32_e32 v111, vcc, 0, v123, vcc
	v_add_co_u32_e32 v114, vcc, s94, v122
	global_load_dwordx4 v[106:109], v[106:107], off nt
	s_nop 0
	global_load_dwordx4 v[110:113], v[110:111], off nt
	v_addc_co_u32_e32 v115, vcc, 0, v123, vcc
	v_add_co_u32_e32 v118, vcc, s2, v122
	v_max3_f32 v134, |v2|, 0, |v6|
	s_nop 0
	v_addc_co_u32_e32 v119, vcc, 0, v123, vcc
	v_add_co_u32_e32 v124, vcc, s95, v122
	global_load_dwordx4 v[114:117], v[114:115], off nt
	s_nop 0
	global_load_dwordx4 v[118:121], v[118:119], off nt
	v_addc_co_u32_e32 v125, vcc, 0, v123, vcc
	v_add_co_u32_e32 v126, vcc, s3, v122
	s_waitcnt vmcnt(16)
	v_max3_f32 v132, v132, |v48|, |v52|
	v_addc_co_u32_e32 v127, vcc, 0, v123, vcc
	global_load_dwordx4 v[122:125], v[124:125], off nt
	s_nop 0
	global_load_dwordx4 v[126:129], v[126:127], off nt
	s_waitcnt vmcnt(2)
; #define LAS __attribute__((address_space(3)))
; __device__ __forceinline__ unsigned pk2(float lo, float hi) { return pg8::cvt_pk_bf16(lo, hi); }
; __device__ __forceinline__ void direct_w8_block(const Ctx& c, LAS unsigned char* lds, const float* Wsrc, const int INC_, int srccol, unsigned char* dstrow, float* swdst) {
;     ...
;     for (int t = 0; t < 8; ++t) { f32x4 v[8]; const float* Wt = W + (size_t)(t * 64) * INC_; asm volatile("" : "+v"(Wt));
; #pragma unroll
;         for (int e = 0; e < 8; ++e) v[e] = __builtin_nontemporal_load((const f32x4*)(Wt + (size_t)e * INC_));
; #pragma unroll
;         for (int j = 0; j < 4; ++j) {
; #pragma unroll
;             for (int e = 0; e < 8; ++e) mx[j] = fmaxf(mx[j], fabsf(v[e][j]));
;             v4u pk; pk.x = pk2(v[0][j], v[1][j]); pk.y = pk2(v[2][j], v[3][j]); pk.z = pk2(v[4][j], v[5][j]); pk.w = pk2(v[6][j], v[7][j]);
;             if (t < 4) { held[t & 3][j][0] = pk.x; held[t & 3][j][1] = pk.y; held[t & 3][j][2] = pk.z; held[t & 3][j][3] = pk.w; }
;             else *(LAS v4u*)(hl + ((t - 4) * 4 + j) * 1024) = pk; }
	v_max3_f32 v134, v134, |v10|, |v14|
	v_max3_f32 v133, v133, |v33|, |v37|
	v_max3_f32 v134, v134, |v18|, |v22|
	v_max3_f32 v132, v132, |v56|, |v60|
	v_max3_f32 v133, v133, |v41|, |v45|
	v_max3_f32 v134, v134, |v26|, |v30|
	v_max3_f32 v135, |v3|, 0, |v7|
	v_max3_f32 v133, v133, |v49|, |v53|
	v_max3_f32 v135, v135, |v11|, |v15|
	v_max3_f32 v133, v133, |v57|, |v61|
	v_max3_f32 v134, v134, |v34|, |v38|
	v_max3_f32 v135, v135, |v19|, |v23|
	v_max3_f32 v134, v134, |v42|, |v46|
	v_max3_f32 v132, v132, |v64|, |v68|
	v_max3_f32 v133, v133, |v65|, |v69|
	v_max3_f32 v135, v135, |v27|, |v31|
	v_max3_f32 v134, v134, |v50|, |v54|
	v_max3_f32 v134, v134, |v58|, |v62|
	v_max3_f32 v135, v135, |v35|, |v39|
	v_max3_f32 v135, v135, |v43|, |v47|
	v_max3_f32 v134, v134, |v66|, |v70|
	v_max3_f32 v135, v135, |v51|, |v55|
	v_max3_f32 v135, v135, |v59|, |v63|
	v_max3_f32 v132, v132, |v72|, |v76|
	v_max3_f32 v133, v133, |v73|, |v77|
	v_max3_f32 v134, v134, |v74|, |v78|
	v_max3_f32 v135, v135, |v67|, |v71|
	v_max3_f32 v135, v135, |v75|, |v79|
	v_max3_f32 v132, v132, |v80|, |v84|
	v_max3_f32 v133, v133, |v81|, |v85|
	v_max3_f32 v134, v134, |v82|, |v86|
	v_max3_f32 v135, v135, |v83|, |v87|
	v_max3_f32 v132, v132, |v88|, |v92|
	v_max3_f32 v133, v133, |v89|, |v93|
	v_max3_f32 v134, v134, |v90|, |v94|
	v_max3_f32 v135, v135, |v91|, |v95|
	v_max3_f32 v132, v132, |v98|, |v102|
	v_max3_f32 v132, v132, |v106|, |v110|
	v_max3_f32 v132, v132, |v114|, |v118|
	s_waitcnt vmcnt(0)
	v_max3_f32 v174, v132, |v122|, |v126|
	v_max3_f32 v132, v133, |v99|, |v103|
	v_max3_f32 v132, v132, |v107|, |v111|
	v_max3_f32 v132, v132, |v115|, |v119|
	v_max3_f32 v178, v132, |v123|, |v127|
	v_max3_f32 v132, v134, |v100|, |v104|
	v_max3_f32 v132, v132, |v108|, |v112|
	v_max3_f32 v132, v132, |v116|, |v120|
	v_max3_f32 v179, v132, |v124|, |v128|
	v_max3_f32 v132, v135, |v101|, |v105|
	v_max3_f32 v132, v132, |v109|, |v113|
	v_max3_f32 v132, v132, |v117|, |v121|
	v_max3_f32 v180, v132, |v125|, |v129|
	s_mov_b64 s[8:9], 0x1800000
	v_lshl_add_u64 v[160:161], v[130:131], 0, s[8:9]
	global_load_dwordx4 v[132:135], v[160:161], off nt
	v_add_co_u32_e32 v136, vcc, s61, v160
	s_mov_b64 s[8:9], 0x1e00000
	s_nop 0
	v_addc_co_u32_e32 v137, vcc, 0, v161, vcc
	v_add_co_u32_e32 v140, vcc, s92, v160
	global_load_dwordx4 v[136:139], v[136:137], off nt
	s_nop 0
	v_addc_co_u32_e32 v141, vcc, 0, v161, vcc
	v_add_co_u32_e32 v144, vcc, s0, v160
	global_load_dwordx4 v[140:143], v[140:141], off nt
	s_nop 0
	v_addc_co_u32_e32 v145, vcc, 0, v161, vcc
	v_add_co_u32_e32 v148, vcc, s94, v160
	global_load_dwordx4 v[144:147], v[144:145], off nt
	s_nop 0
	v_addc_co_u32_e32 v149, vcc, 0, v161, vcc
	v_add_co_u32_e32 v152, vcc, s2, v160
	global_load_dwordx4 v[148:151], v[148:149], off nt
	s_nop 0
	v_addc_co_u32_e32 v153, vcc, 0, v161, vcc
	v_add_co_u32_e32 v156, vcc, s95, v160
	global_load_dwordx4 v[152:155], v[152:153], off nt
	s_nop 0
	v_addc_co_u32_e32 v157, vcc, 0, v161, vcc
	v_add_co_u32_e32 v160, vcc, s3, v160
	global_load_dwordx4 v[156:159], v[156:157], off nt
	s_nop 0
	v_addc_co_u32_e32 v161, vcc, 0, v161, vcc
	global_load_dwordx4 v[170:173], v[160:161], off nt
	s_waitcnt vmcnt(0) lgkmcnt(0)
	v_max3_f32 v160, v174, |v132|, |v136|
	v_cvt_pk_bf16_f32 v174, v132, v136
	v_max3_f32 v132, v178, |v133|, |v137|
	v_max3_f32 v132, v132, |v141|, |v145|
	v_max3_f32 v160, v160, |v140|, |v144|
	v_cvt_pk_bf16_f32 v175, v140, v144
	v_max3_f32 v132, v132, |v149|, |v153|
	v_cvt_pk_bf16_f32 v176, v148, v152
	v_max3_f32 v160, v160, |v148|, |v152|
	v_cvt_pk_bf16_f32 v144, v151, v155
	v_max3_f32 v178, v132, |v157|, |v171|
	v_max3_f32 v132, v179, |v134|, |v138|
	v_max3_f32 v132, v132, |v142|, |v146|
	v_cvt_pk_bf16_f32 v177, v156, v170
	v_max3_f32 v132, v132, |v150|, |v154|
	ds_write_b128 v96, v[174:177]
	v_cvt_pk_bf16_f32 v177, v157, v171
	v_cvt_pk_bf16_f32 v176, v149, v153
	v_cvt_pk_bf16_f32 v175, v141, v145
	v_cvt_pk_bf16_f32 v174, v133, v137
	v_max3_f32 v179, v132, |v158|, |v172|
	v_max3_f32 v132, v180, |v135|, |v139|
	v_max3_f32 v181, v160, |v156|, |v170|
	ds_write_b128 v96, v[174:177] offset:1024
	v_cvt_pk_bf16_f32 v177, v158, v172
	v_cvt_pk_bf16_f32 v176, v150, v154
	v_cvt_pk_bf16_f32 v175, v142, v146
	v_cvt_pk_bf16_f32 v174, v134, v138
	v_max3_f32 v132, v132, |v143|, |v147|
	v_cvt_pk_bf16_f32 v145, v159, v173
	v_cvt_pk_bf16_f32 v143, v143, v147
	v_cvt_pk_bf16_f32 v142, v135, v139
	v_lshl_add_u64 v[160:161], v[130:131], 0, s[8:9]
	ds_write_b128 v96, v[174:177] offset:2048
	ds_write_b128 v96, v[142:145] offset:3072
	v_max3_f32 v132, v132, |v151|, |v155|
	v_add_co_u32_e32 v136, vcc, s61, v160
	v_max3_f32 v180, v132, |v159|, |v173|
	s_nop 0
	v_addc_co_u32_e32 v137, vcc, 0, v161, vcc
	v_add_co_u32_e32 v140, vcc, s92, v160
	global_load_dwordx4 v[132:135], v[160:161], off nt
	s_nop 0
	v_addc_co_u32_e32 v141, vcc, 0, v161, vcc
	v_add_co_u32_e32 v144, vcc, s0, v160
	global_load_dwordx4 v[136:139], v[136:137], off nt
	s_nop 0
	v_addc_co_u32_e32 v145, vcc, 0, v161, vcc
	v_add_co_u32_e32 v148, vcc, s94, v160
	global_load_dwordx4 v[140:143], v[140:141], off nt
	s_nop 0
	v_addc_co_u32_e32 v149, vcc, 0, v161, vcc
	v_add_co_u32_e32 v152, vcc, s2, v160
	global_load_dwordx4 v[144:147], v[144:145], off nt
	s_nop 0
	v_addc_co_u32_e32 v153, vcc, 0, v161, vcc
	v_add_co_u32_e32 v156, vcc, s95, v160
	global_load_dwordx4 v[148:151], v[148:149], off nt
	s_nop 0
	v_addc_co_u32_e32 v157, vcc, 0, v161, vcc
	v_add_co_u32_e32 v160, vcc, s3, v160
	global_load_dwordx4 v[152:155], v[152:153], off nt
	s_nop 0
	v_addc_co_u32_e32 v161, vcc, 0, v161, vcc
	global_load_dwordx4 v[156:159], v[156:157], off nt
	s_mov_b64 s[8:9], 0x2400000
	global_load_dwordx4 v[170:173], v[160:161], off nt
	s_waitcnt vmcnt(0) lgkmcnt(0)
; #define LAS __attribute__((address_space(3)))
; __device__ __forceinline__ unsigned pk2(float lo, float hi) { return pg8::cvt_pk_bf16(lo, hi); }
; __device__ __forceinline__ void direct_w8_block(const Ctx& c, LAS unsigned char* lds, const float* Wsrc, const int INC_, int srccol, unsigned char* dstrow, float* swdst) {
;     ...
;     for (int t = 0; t < 8; ++t) { f32x4 v[8]; const float* Wt = W + (size_t)(t * 64) * INC_; asm volatile("" : "+v"(Wt));
; #pragma unroll
;         for (int e = 0; e < 8; ++e) v[e] = __builtin_nontemporal_load((const f32x4*)(Wt + (size_t)e * INC_));
; #pragma unroll
;         for (int j = 0; j < 4; ++j) {
; #pragma unroll
;             for (int e = 0; e < 8; ++e) mx[j] = fmaxf(mx[j], fabsf(v[e][j]));
;             v4u pk; pk.x = pk2(v[0][j], v[1][j]); pk.y = pk2(v[2][j], v[3][j]); pk.z = pk2(v[4][j], v[5][j]); pk.w = pk2(v[6][j], v[7][j]);
;             if (t < 4) { held[t & 3][j][0] = pk.x; held[t & 3][j][1] = pk.y; held[t & 3][j][2] = pk.z; held[t & 3][j][3] = pk.w; }
;             else *(LAS v4u*)(hl + ((t - 4) * 4 + j) * 1024) = pk; }
	v_max3_f32 v160, v181, |v132|, |v136|
	v_cvt_pk_bf16_f32 v174, v132, v136
	v_max3_f32 v132, v178, |v133|, |v137|
	v_max3_f32 v160, v160, |v140|, |v144|
	v_max3_f32 v132, v132, |v141|, |v145|
	v_cvt_pk_bf16_f32 v175, v140, v144
	v_max3_f32 v160, v160, |v148|, |v152|
	v_max3_f32 v132, v132, |v149|, |v153|
	v_cvt_pk_bf16_f32 v176, v148, v152
	v_cvt_pk_bf16_f32 v144, v151, v155
	v_max3_f32 v181, v160, |v156|, |v170|
	v_cvt_pk_bf16_f32 v177, v156, v170
	v_max3_f32 v170, v132, |v157|, |v171|
	v_max3_f32 v132, v179, |v134|, |v138|
	v_max3_f32 v132, v132, |v142|, |v146|
	v_max3_f32 v132, v132, |v150|, |v154|
	ds_write_b128 v96, v[174:177] offset:4096
	v_cvt_pk_bf16_f32 v177, v157, v171
	v_cvt_pk_bf16_f32 v176, v149, v153
	v_cvt_pk_bf16_f32 v175, v141, v145
	v_cvt_pk_bf16_f32 v174, v133, v137
	v_max3_f32 v171, v132, |v158|, |v172|
	v_max3_f32 v132, v180, |v135|, |v139|
	ds_write_b128 v96, v[174:177] offset:5120
	v_cvt_pk_bf16_f32 v177, v158, v172
	v_cvt_pk_bf16_f32 v176, v150, v154
	v_cvt_pk_bf16_f32 v175, v142, v146
	v_cvt_pk_bf16_f32 v174, v134, v138
	v_max3_f32 v132, v132, |v143|, |v147|
	v_cvt_pk_bf16_f32 v145, v159, v173
	v_cvt_pk_bf16_f32 v143, v143, v147
	v_cvt_pk_bf16_f32 v142, v135, v139
	v_lshl_add_u64 v[160:161], v[130:131], 0, s[8:9]
	ds_write_b128 v96, v[174:177] offset:6144
	ds_write_b128 v96, v[142:145] offset:7168
	v_max3_f32 v132, v132, |v151|, |v155|
	v_add_co_u32_e32 v136, vcc, s61, v160
	v_max3_f32 v182, v132, |v159|, |v173|
	s_nop 0
	v_addc_co_u32_e32 v137, vcc, 0, v161, vcc
	v_add_co_u32_e32 v140, vcc, s92, v160
	global_load_dwordx4 v[132:135], v[160:161], off nt
	s_nop 0
	v_addc_co_u32_e32 v141, vcc, 0, v161, vcc
	v_add_co_u32_e32 v144, vcc, s0, v160
	global_load_dwordx4 v[136:139], v[136:137], off nt
	s_nop 0
	v_addc_co_u32_e32 v145, vcc, 0, v161, vcc
	v_add_co_u32_e32 v148, vcc, s94, v160
	global_load_dwordx4 v[140:143], v[140:141], off nt
	s_nop 0
	v_addc_co_u32_e32 v149, vcc, 0, v161, vcc
	v_add_co_u32_e32 v152, vcc, s2, v160
	global_load_dwordx4 v[144:147], v[144:145], off nt
	s_nop 0
	v_addc_co_u32_e32 v153, vcc, 0, v161, vcc
	v_add_co_u32_e32 v156, vcc, s95, v160
	global_load_dwordx4 v[148:151], v[148:149], off nt
	s_nop 0
	v_addc_co_u32_e32 v157, vcc, 0, v161, vcc
	v_add_co_u32_e32 v160, vcc, s3, v160
	global_load_dwordx4 v[152:155], v[152:153], off nt
	s_nop 0
	v_addc_co_u32_e32 v161, vcc, 0, v161, vcc
	global_load_dwordx4 v[156:159], v[156:157], off nt
	s_mov_b64 s[8:9], 0x2a00000
	global_load_dwordx4 v[174:177], v[160:161], off nt
	s_waitcnt vmcnt(0) lgkmcnt(0)
	v_max3_f32 v160, v181, |v132|, |v136|
	v_cvt_pk_bf16_f32 v178, v132, v136
	v_max3_f32 v132, v170, |v133|, |v137|
	v_max3_f32 v132, v132, |v141|, |v145|
	v_cvt_pk_bf16_f32 v179, v140, v144
	v_max3_f32 v160, v160, |v140|, |v144|
	v_max3_f32 v132, v132, |v149|, |v153|
	v_cvt_pk_bf16_f32 v180, v148, v152
	v_cvt_pk_bf16_f32 v144, v151, v155
	v_max3_f32 v160, v160, |v148|, |v152|
	v_max3_f32 v172, v132, |v157|, |v175|
	v_max3_f32 v132, v171, |v134|, |v138|
	v_max3_f32 v132, v132, |v142|, |v146|
	v_max3_f32 v132, v132, |v150|, |v154|
	v_max3_f32 v171, v132, |v158|, |v176|
	v_max3_f32 v132, v182, |v135|, |v139|
	v_cvt_pk_bf16_f32 v181, v156, v174
	v_max3_f32 v132, v132, |v143|, |v147|
	ds_write_b128 v96, v[178:181] offset:8192
	v_cvt_pk_bf16_f32 v181, v157, v175
	v_cvt_pk_bf16_f32 v180, v149, v153
	v_cvt_pk_bf16_f32 v179, v141, v145
	v_cvt_pk_bf16_f32 v178, v133, v137
	v_max3_f32 v132, v132, |v151|, |v155|
	ds_write_b128 v96, v[178:181] offset:9216
	v_cvt_pk_bf16_f32 v181, v158, v176
	v_cvt_pk_bf16_f32 v180, v150, v154
	v_cvt_pk_bf16_f32 v179, v142, v146
	v_cvt_pk_bf16_f32 v178, v134, v138
	v_max3_f32 v170, v132, |v159|, |v177|
	v_cvt_pk_bf16_f32 v145, v159, v177
	v_cvt_pk_bf16_f32 v143, v143, v147
	v_cvt_pk_bf16_f32 v142, v135, v139
	v_lshl_add_u64 v[158:159], v[130:131], 0, s[8:9]
	ds_write_b128 v96, v[178:181] offset:10240
	ds_write_b128 v96, v[142:145] offset:11264
	global_load_dwordx4 v[130:133], v[158:159], off nt
	v_add_co_u32_e32 v134, vcc, s61, v158
	v_max3_f32 v173, v160, |v156|, |v174|
	s_nop 0
	v_addc_co_u32_e32 v135, vcc, 0, v159, vcc
	v_add_co_u32_e32 v138, vcc, s92, v158
	global_load_dwordx4 v[134:137], v[134:135], off nt
	s_nop 0
	v_addc_co_u32_e32 v139, vcc, 0, v159, vcc
	v_add_co_u32_e32 v142, vcc, s0, v158
	global_load_dwordx4 v[138:141], v[138:139], off nt
	s_nop 0
	v_addc_co_u32_e32 v143, vcc, 0, v159, vcc
	v_add_co_u32_e32 v146, vcc, s94, v158
	global_load_dwordx4 v[142:145], v[142:143], off nt
	s_nop 0
	v_addc_co_u32_e32 v147, vcc, 0, v159, vcc
	v_add_co_u32_e32 v150, vcc, s2, v158
	global_load_dwordx4 v[146:149], v[146:147], off nt
	s_nop 0
	v_addc_co_u32_e32 v151, vcc, 0, v159, vcc
	v_add_co_u32_e32 v154, vcc, s95, v158
	global_load_dwordx4 v[150:153], v[150:151], off nt
	s_nop 0
	v_addc_co_u32_e32 v155, vcc, 0, v159, vcc
	v_add_co_u32_e32 v158, vcc, s3, v158
	global_load_dwordx4 v[154:157], v[154:155], off nt
	s_nop 0
	v_addc_co_u32_e32 v159, vcc, 0, v159, vcc
	global_load_dwordx4 v[158:161], v[158:159], off nt
	s_waitcnt vmcnt(0) lgkmcnt(0)
; #define LAS __attribute__((address_space(3)))
; __device__ __forceinline__ unsigned pk2(float lo, float hi) { return pg8::cvt_pk_bf16(lo, hi); }
; __device__ __forceinline__ void direct_w8_block(const Ctx& c, LAS unsigned char* lds, const float* Wsrc, const int INC_, int srccol, unsigned char* dstrow, float* swdst) {
;     ...
;     for (int t = 0; t < 8; ++t) { f32x4 v[8]; const float* Wt = W + (size_t)(t * 64) * INC_; asm volatile("" : "+v"(Wt));
; #pragma unroll
;         for (int e = 0; e < 8; ++e) v[e] = __builtin_nontemporal_load((const f32x4*)(Wt + (size_t)e * INC_));
; #pragma unroll
;         for (int j = 0; j < 4; ++j) {
; #pragma unroll
;             for (int e = 0; e < 8; ++e) mx[j] = fmaxf(mx[j], fabsf(v[e][j]));
;             v4u pk; pk.x = pk2(v[0][j], v[1][j]); pk.y = pk2(v[2][j], v[3][j]); pk.z = pk2(v[4][j], v[5][j]); pk.w = pk2(v[6][j], v[7][j]);
;             if (t < 4) { held[t & 3][j][0] = pk.x; held[t & 3][j][1] = pk.y; held[t & 3][j][2] = pk.z; held[t & 3][j][3] = pk.w; }
;             else *(LAS v4u*)(hl + ((t - 4) * 4 + j) * 1024) = pk; }
;         if ((t & 3) == 3) { asm volatile("" ::: "memory"); __builtin_amdgcn_sched_barrier(0); } }
; #pragma unroll
;     for (int j = 0; j < 4; ++j) { float m = mx[j]; m = fmaxf(m, __shfl_xor(m, 8)); m = fmaxf(m, __shfl_xor(m, 16)); m = fmaxf(m, __shfl_xor(m, 32)); mx[j] = m; }
;     if (kr == 0) *(LAS f32x4*)(pm + wave * 32 + 4 * nc) = mx;
	v_max3_f32 v173, v173, |v130|, |v134|
	v_cvt_pk_bf16_f32 v174, v130, v134
	v_max3_f32 v130, v172, |v131|, |v135|
	v_cvt_pk_bf16_f32 v172, v131, v135
	v_max3_f32 v131, v171, |v132|, |v136|
	v_max3_f32 v173, v173, |v138|, |v142|
	v_max3_f32 v131, v131, |v140|, |v144|
	v_cvt_pk_bf16_f32 v175, v138, v142
	v_max3_f32 v130, v130, |v139|, |v143|
	v_max3_f32 v173, v173, |v146|, |v150|
	v_cvt_pk_bf16_f32 v176, v146, v150
	v_max3_f32 v131, v131, |v148|, |v152|
	v_cvt_pk_bf16_f32 v142, v149, v153
	v_max3_f32 v130, v130, |v147|, |v151|
	v_cvt_pk_bf16_f32 v177, v154, v158
	v_max3_f32 v178, v173, |v154|, |v158|
	ds_write_b128 v96, v[174:177] offset:12288
	v_cvt_pk_bf16_f32 v175, v155, v159
	v_cvt_pk_bf16_f32 v174, v147, v151
	v_cvt_pk_bf16_f32 v173, v139, v143
	v_max3_f32 v134, v131, |v156|, |v160|
	v_max3_f32 v131, v170, |v133|, |v137|
	ds_write_b128 v96, v[172:175] offset:13312
	v_cvt_pk_bf16_f32 v175, v156, v160
	v_cvt_pk_bf16_f32 v174, v148, v152
	v_cvt_pk_bf16_f32 v173, v140, v144
	v_cvt_pk_bf16_f32 v172, v132, v136
	v_max3_f32 v131, v131, |v141|, |v145|
	v_cvt_pk_bf16_f32 v143, v157, v161
	v_cvt_pk_bf16_f32 v141, v141, v145
	v_cvt_pk_bf16_f32 v140, v133, v137
	ds_write_b128 v96, v[172:175] offset:14336
	ds_write_b128 v96, v[140:143] offset:15360
	v_max3_f32 v131, v131, |v149|, |v153|
	v_max3_f32 v130, v130, |v155|, |v159|
	v_max3_f32 v135, v131, |v157|, |v161|
	v_and_b32_e32 v132, 64, v238
	v_xor_b32_e32 v131, 8, v238
	v_add_u32_e32 v132, 64, v132
	v_cmp_lt_i32_e32 vcc, v131, v132
	v_xor_b32_e32 v137, 32, v238
	s_nop 0
	v_cndmask_b32_e32 v131, v238, v131, vcc
	v_lshlrev_b32_e32 v133, 2, v131
	v_xor_b32_e32 v131, 16, v238
	v_cmp_lt_i32_e32 vcc, v131, v132
	s_nop 1
	v_cndmask_b32_e32 v131, v238, v131, vcc
	v_lshlrev_b32_e32 v136, 2, v131
	ds_bpermute_b32 v131, v133, v178
	v_cmp_lt_i32_e32 vcc, v137, v132
	s_waitcnt lgkmcnt(0)
	v_max_f32_e32 v131, v131, v131
	v_cndmask_b32_e32 v132, v238, v137, vcc
	ds_bpermute_b32 v137, v133, v130
	v_max_f32_e32 v131, v178, v131
	ds_bpermute_b32 v138, v136, v131
	v_lshlrev_b32_e32 v139, 2, v132
	s_waitcnt lgkmcnt(1)
	v_max_f32_e32 v132, v137, v137
	v_max_f32_e32 v132, v130, v132
	ds_bpermute_b32 v137, v136, v132
	s_waitcnt lgkmcnt(1)
	v_max_f32_e32 v130, v138, v138
	ds_bpermute_b32 v138, v133, v134
	ds_bpermute_b32 v133, v133, v135
	v_max_f32_e32 v130, v131, v130
	s_waitcnt lgkmcnt(2)
	v_max_f32_e32 v137, v137, v137
	v_max_f32_e32 v132, v132, v137
	s_waitcnt lgkmcnt(1)
	v_max_f32_e32 v137, v138, v138
	s_waitcnt lgkmcnt(0)
	v_max_f32_e32 v133, v133, v133
	v_max_f32_e32 v137, v134, v137
	v_max_f32_e32 v140, v135, v133
	ds_bpermute_b32 v138, v136, v137
	ds_bpermute_b32 v136, v136, v140
	ds_bpermute_b32 v131, v139, v130
	ds_bpermute_b32 v134, v139, v132
	s_waitcnt lgkmcnt(3)
	v_max_f32_e32 v133, v138, v138
	s_waitcnt lgkmcnt(2)
	v_max_f32_e32 v136, v136, v136
	v_max_f32_e32 v133, v137, v133
	v_max_f32_e32 v136, v140, v136
	ds_bpermute_b32 v135, v139, v133
	ds_bpermute_b32 v137, v139, v136
	s_and_saveexec_b64 s[8:9], s[6:7]
	s_cbranch_execz .LBB0_455
	s_waitcnt lgkmcnt(0)
	v_max_f32_e32 v137, v137, v137
	v_max_f32_e32 v136, v136, v136
	v_max_f32_e32 v131, v131, v131
	v_max_f32_e32 v130, v130, v130
	v_max_f32_e32 v139, v136, v137
	v_max_f32_e32 v136, v130, v131
	v_max_f32_e32 v130, v134, v134
	v_max_f32_e32 v131, v132, v132
	v_max_f32_e32 v137, v131, v130
	v_max_f32_e32 v130, v135, v135
	v_max_f32_e32 v131, v133, v133
	v_max_f32_e32 v138, v131, v130
	ds_write_b128 v168, v[136:139]
